# GEMM K-loops: first trip of every non-first unit peeled with vmcnt waits that leave the previous epilogue's stores in flight
# speedup vs baseline: 1.0091x; 1.0091x over previous
; #define PG8_STAGE(bufoff, gbase, voff) do { _Pragma("unroll") for (int _i = 0; _i < 2; ++_i) \
;         __builtin_amdgcn_global_load_lds((const unsigned*)((const char*)(gbase) + (voff)[_i]), (PG8_LAS unsigned*)(lds + (bufoff) + ldsw + _i * 8192), 16, 0, 0); } while (0)
; #define PG8_LDA(dst, b, h) do { _Pragma("unroll") for (int m = 0; m < 4; ++m) _Pragma("unroll") for (int k = 0; k < 2; ++k) dst[m][k] = *(const PG8_LAS bf16x8*)(lds + PG8_SA(b, h) + aoff + m * 2048 + k * 1024); } while (0)
; #define PG8_LDB(dst, b, h) do { _Pragma("unroll") for (int n = 0; n < 2; ++n) _Pragma("unroll") for (int k = 0; k < 2; ++k) dst[n][k] = *(const PG8_LAS bf16x8*)(lds + PG8_SB(b, h) + boff + n * 2048 + k * 1024); } while (0)
; #define PG8_WAIT_V(n) asm volatile("s_waitcnt vmcnt(" #n ")" ::: "memory")
; #define PG8_WAIT_L(n) asm volatile("s_waitcnt lgkmcnt(" #n ")" ::: "memory")
; #define PG8_BAR __builtin_amdgcn_s_barrier()
; #define PG8_SCHED __builtin_amdgcn_sched_barrier(0)
; template <class Epi, class Sched, bool ALIGN_EPI = false, bool SP2 = false>
; __device__ __forceinline__ void gemm_phase(PG8_LAS unsigned char* lds, const Gemm g, const Sched& S, const Epi& E) {
;     ...
;         const bool has_next = S.next(ui + 1, nxt);
;         const char* nA = has_next ? (const char*)g.A + (size_t)nxt.pm * tstep : cA; const char* nB = has_next ? (const char*)g.Bt + (size_t)nxt.pn * tstep : cB;
;         for (int t = 0; t < nt; t += 2) {
;             const bool last = (t == nt - 2);
;             const char* a1 = cA + (size_t)(t + 1) * kstep;
;             const char* a2 = last ? nA : cA + (size_t)(t + 2) * kstep; const char* b2 = last ? nB : cB + (size_t)(t + 2) * kstep;
;             const char* a3 = a2 + kstep; const char* b3 = b2 + kstep;
;             if (last && has_next) S.a_ready(nxt);
;             if constexpr (SP2) {
;             PG8_LDB(B0, 0, 0); PG8_LDB(B1, 0, 1); PG8_SCHED; PG8_LDA(At, 0, 0); PG8_STAGE(PG8_SA(1, 1), a1 + hstep, voffA);
;             PG8_WAIT_V(8); PG8_WAIT_L(0); PG8_BAR; PG8_MMA(0, 0, At, B0); PG8_MMA(0, 1, At, B1); PG8_BAR; PG8_SCHED;
;     ...
;         for (int a = 0; a < 2; ++a)
; #pragma unroll
;             for (int b = 0; b < 2; ++b)
; #pragma unroll
;                 for (int m = 0; m < 4; ++m)
; #pragma unroll
;                     for (int n = 0; n < 2; ++n) acc[a][b][m][n] = (f32x4){0.f, 0.f, 0.f, 0.f};
;         cur = nxt; cA = nA; cB = nB; ++ui;
.LBB0_82:
	s_ashr_i32 s67, s66, 31
	s_lshl_b64 s[4:5], s[66:67], 19
	s_add_u32 s26, s60, s4
	s_addc_u32 s27, s61, s5
	s_and_b64 s[4:5], s[86:87], exec
	s_cselect_b32 s7, s27, s71
	s_cselect_b32 s11, s26, s70
	s_ashr_i32 s69, s68, 31
	s_lshl_b64 s[4:5], s[68:69], 19
	s_add_u32 s50, s3, s4
	s_addc_u32 s51, s13, s5
	s_and_b64 s[4:5], s[86:87], exec
	s_cselect_b32 s23, s51, s99
	s_cselect_b32 s69, s50, s98
	s_add_u32 vcc_lo, s70, 0x40080
	s_addc_u32 vcc_hi, s71, 0
	s_add_u32 s46, s98, 0x100
	v_mov_b32_e32 v0, 0
	s_addc_u32 s47, s99, 0
	s_mov_b32 s4, -2
	v_mov_b32_e32 v1, v0
	v_mov_b32_e32 v2, v0
	v_mov_b32_e32 v3, v0
	v_mov_b32_e32 v8, v0
	v_mov_b32_e32 v9, v0
	v_mov_b32_e32 v10, v0
	v_mov_b32_e32 v11, v0
	v_mov_b32_e32 v16, v0
	v_mov_b32_e32 v17, v0
	v_mov_b32_e32 v18, v0
	v_mov_b32_e32 v19, v0
	v_mov_b32_e32 v24, v0
	v_mov_b32_e32 v25, v0
	v_mov_b32_e32 v26, v0
	v_mov_b32_e32 v27, v0
	v_mov_b32_e32 v32, v0
	v_mov_b32_e32 v33, v0
	v_mov_b32_e32 v34, v0
	v_mov_b32_e32 v35, v0
	v_mov_b32_e32 v40, v0
	v_mov_b32_e32 v41, v0
	v_mov_b32_e32 v42, v0
	v_mov_b32_e32 v43, v0
	v_mov_b32_e32 v48, v0
	v_mov_b32_e32 v49, v0
	v_mov_b32_e32 v50, v0
	v_mov_b32_e32 v51, v0
	v_mov_b32_e32 v56, v0
	v_mov_b32_e32 v57, v0
	v_mov_b32_e32 v58, v0
	v_mov_b32_e32 v59, v0
	v_mov_b32_e32 v4, v0
	v_mov_b32_e32 v5, v0
	v_mov_b32_e32 v6, v0
	v_mov_b32_e32 v7, v0
	v_mov_b32_e32 v12, v0
	v_mov_b32_e32 v13, v0
	v_mov_b32_e32 v14, v0
	v_mov_b32_e32 v15, v0
	v_mov_b32_e32 v20, v0
	v_mov_b32_e32 v21, v0
	v_mov_b32_e32 v22, v0
	v_mov_b32_e32 v23, v0
	v_mov_b32_e32 v28, v0
	v_mov_b32_e32 v29, v0
	v_mov_b32_e32 v30, v0
	v_mov_b32_e32 v31, v0
	v_mov_b32_e32 v36, v0
	v_mov_b32_e32 v37, v0
	v_mov_b32_e32 v38, v0
	v_mov_b32_e32 v39, v0
	v_mov_b32_e32 v44, v0
	v_mov_b32_e32 v45, v0
	v_mov_b32_e32 v46, v0
	v_mov_b32_e32 v47, v0
	v_mov_b32_e32 v52, v0
	v_mov_b32_e32 v53, v0
	v_mov_b32_e32 v54, v0
	v_mov_b32_e32 v55, v0
	v_mov_b32_e32 v60, v0
	v_mov_b32_e32 v61, v0
	v_mov_b32_e32 v62, v0
	v_mov_b32_e32 v63, v0
	v_mov_b32_e32 v64, v0
	v_mov_b32_e32 v65, v0
	v_mov_b32_e32 v66, v0
	v_mov_b32_e32 v67, v0
	v_mov_b32_e32 v72, v0
	v_mov_b32_e32 v73, v0
	v_mov_b32_e32 v74, v0
	v_mov_b32_e32 v75, v0
	v_mov_b32_e32 v80, v0
	v_mov_b32_e32 v81, v0
	v_mov_b32_e32 v82, v0
	v_mov_b32_e32 v83, v0
	v_mov_b32_e32 v88, v0
	v_mov_b32_e32 v89, v0
	v_mov_b32_e32 v90, v0
	v_mov_b32_e32 v91, v0
	v_mov_b32_e32 v96, v0
	v_mov_b32_e32 v97, v0
	v_mov_b32_e32 v98, v0
	v_mov_b32_e32 v99, v0
	v_mov_b32_e32 v104, v0
	v_mov_b32_e32 v105, v0
	v_mov_b32_e32 v106, v0
	v_mov_b32_e32 v107, v0
	v_mov_b32_e32 v112, v0
	v_mov_b32_e32 v113, v0
	v_mov_b32_e32 v114, v0
	v_mov_b32_e32 v115, v0
	v_mov_b32_e32 v120, v0
	v_mov_b32_e32 v121, v0
	v_mov_b32_e32 v122, v0
	v_mov_b32_e32 v123, v0
	v_mov_b32_e32 v68, v0
	v_mov_b32_e32 v69, v0
	v_mov_b32_e32 v70, v0
	v_mov_b32_e32 v71, v0
	v_mov_b32_e32 v76, v0
	v_mov_b32_e32 v77, v0
	v_mov_b32_e32 v78, v0
	v_mov_b32_e32 v79, v0
	v_mov_b32_e32 v84, v0
	v_mov_b32_e32 v85, v0
	v_mov_b32_e32 v86, v0
	v_mov_b32_e32 v87, v0
	v_mov_b32_e32 v92, v0
	v_mov_b32_e32 v93, v0
	v_mov_b32_e32 v94, v0
	v_mov_b32_e32 v95, v0
	v_mov_b32_e32 v100, v0
	v_mov_b32_e32 v101, v0
	v_mov_b32_e32 v102, v0
	v_mov_b32_e32 v103, v0
	v_mov_b32_e32 v108, v0
	v_mov_b32_e32 v109, v0
	v_mov_b32_e32 v110, v0
	v_mov_b32_e32 v111, v0
	v_mov_b32_e32 v116, v0
	v_mov_b32_e32 v117, v0
	v_mov_b32_e32 v118, v0
	v_mov_b32_e32 v119, v0
	v_mov_b32_e32 v124, v0
	v_mov_b32_e32 v125, v0
	v_mov_b32_e32 v126, v0
	v_mov_b32_e32 v127, v0
	s_cmp_eq_u32 s22, 1
	s_cbranch_scc1 .LBB0_83
	s_add_u32 s5, vcc_lo, 0xfffc0080
	s_addc_u32 s25, vcc_hi, -1
	s_add_i32 s19, 0, 0x10000
	s_cmp_eq_u32 s4, 12
	s_cselect_b32 s99, s7, s25
	s_cselect_b32 s98, s11, s5
	v_add_u32_e32 v151, s19, v141
	s_cselect_b32 s71, s23, s47
	s_cselect_b32 s70, s69, s46
	s_add_i32 s25, 0, 0x14000
	ds_read_b128 v[152:155], v151
	ds_read_b128 v[156:159], v151 offset:1024
	ds_read_b128 v[162:165], v151 offset:2048
	ds_read_b128 v[166:169], v151 offset:3072
	v_add_u32_e32 v151, s25, v141
	ds_read_b128 v[172:175], v151
	ds_read_b128 v[176:179], v151 offset:1024
	ds_read_b128 v[180:183], v151 offset:2048
	ds_read_b128 v[184:187], v151 offset:3072
	v_lshl_add_u64 v[238:239], vcc, 0, v[136:137]
	s_add_i32 m0, s81, 0xc000
	ds_read_b128 v[188:191], v150
	ds_read_b128 v[192:195], v150 offset:1024
	ds_read_b128 v[196:199], v150 offset:2048
	ds_read_b128 v[218:221], v150 offset:3072
	ds_read_b128 v[222:225], v150 offset:4096
	ds_read_b128 v[226:229], v150 offset:5120
	ds_read_b128 v[230:233], v150 offset:6144
	ds_read_b128 v[234:237], v150 offset:7168
	global_load_lds_dwordx4 v[238:239], off
	v_lshl_add_u64 v[238:239], vcc, 0, v[138:139]
	s_add_i32 m0, s81, 0xe000
	s_nop 0
	global_load_lds_dwordx4 v[238:239], off
	s_waitcnt vmcnt(16)
	s_waitcnt lgkmcnt(0)
	s_barrier
; #define PG8_STAGE(bufoff, gbase, voff) do { _Pragma("unroll") for (int _i = 0; _i < 2; ++_i) \
;         __builtin_amdgcn_global_load_lds((const unsigned*)((const char*)(gbase) + (voff)[_i]), (PG8_LAS unsigned*)(lds + (bufoff) + ldsw + _i * 8192), 16, 0, 0); } while (0)
; #define PG8_LDA(dst, b, h) do { _Pragma("unroll") for (int m = 0; m < 4; ++m) _Pragma("unroll") for (int k = 0; k < 2; ++k) dst[m][k] = *(const PG8_LAS bf16x8*)(lds + PG8_SA(b, h) + aoff + m * 2048 + k * 1024); } while (0)
; #define PG8_LDB(dst, b, h) do { _Pragma("unroll") for (int n = 0; n < 2; ++n) _Pragma("unroll") for (int k = 0; k < 2; ++k) dst[n][k] = *(const PG8_LAS bf16x8*)(lds + PG8_SB(b, h) + boff + n * 2048 + k * 1024); } while (0)
; #define PG8_MMA(ai, bj, At, Bt) do { __builtin_amdgcn_s_setprio(1); _Pragma("unroll") for (int m = 0; m < 4; ++m) _Pragma("unroll") for (int n = 0; n < 2; ++n) _Pragma("unroll") for (int k = 0; k < 2; ++k) \
;         acc[ai][bj][m][n] = __builtin_amdgcn_mfma_f32_16x16x32_bf16(Bt[n][k], At[m][k], acc[ai][bj][m][n], 0, 0, 0); __builtin_amdgcn_s_setprio(0); } while (0)
; #define PG8_WAIT_V(n) asm volatile("s_waitcnt vmcnt(" #n ")" ::: "memory")
; #define PG8_WAIT_L(n) asm volatile("s_waitcnt lgkmcnt(" #n ")" ::: "memory")
; #define PG8_BAR __builtin_amdgcn_s_barrier()
; #define PG8_SCHED __builtin_amdgcn_sched_barrier(0)
; template <class Epi, class Sched, bool ALIGN_EPI = false, bool SP2 = false>
; __device__ __forceinline__ void gemm_phase(PG8_LAS unsigned char* lds, const Gemm g, const Sched& S, const Epi& E) {
;     ...
;             PG8_LDB(B0, 0, 0); PG8_LDB(B1, 0, 1); PG8_SCHED; PG8_LDA(At, 0, 0); PG8_STAGE(PG8_SA(1, 1), a1 + hstep, voffA);
;             PG8_WAIT_V(8); PG8_WAIT_L(0); PG8_BAR; PG8_MMA(0, 0, At, B0); PG8_MMA(0, 1, At, B1); PG8_BAR; PG8_SCHED;
;             PG8_LDA(At, 0, 1); PG8_STAGE(PG8_SB(0, 0), b2, voffB); PG8_STAGE(PG8_SB(0, 1), b2 + hstep, voffB); PG8_STAGE(PG8_SA(0, 0), a2, voffA);
;             PG8_WAIT_V(8); PG8_WAIT_L(0); PG8_BAR; PG8_MMA(1, 0, At, B0); PG8_MMA(1, 1, At, B1); PG8_BAR; PG8_SCHED;
	s_setprio 1
	s_waitcnt lgkmcnt(0)
	v_mfma_f32_16x16x32_bf16 v[124:127], v[152:155], v[188:191], v[124:127]
	v_mfma_f32_16x16x32_bf16 v[116:119], v[162:165], v[188:191], v[116:119]
	v_mfma_f32_16x16x32_bf16 v[108:111], v[152:155], v[196:199], v[108:111]
	v_mfma_f32_16x16x32_bf16 v[100:103], v[162:165], v[196:199], v[100:103]
	v_mfma_f32_16x16x32_bf16 v[92:95], v[152:155], v[222:225], v[92:95]
	v_mfma_f32_16x16x32_bf16 v[84:87], v[162:165], v[222:225], v[84:87]
	v_mfma_f32_16x16x32_bf16 v[76:79], v[152:155], v[230:233], v[76:79]
	v_mfma_f32_16x16x32_bf16 v[68:71], v[162:165], v[230:233], v[68:71]
	v_mfma_f32_16x16x32_bf16 v[124:127], v[156:159], v[192:195], v[124:127]
	v_mfma_f32_16x16x32_bf16 v[116:119], v[166:169], v[192:195], v[116:119]
	v_mfma_f32_16x16x32_bf16 v[108:111], v[156:159], v[218:221], v[108:111]
	v_mfma_f32_16x16x32_bf16 v[100:103], v[166:169], v[218:221], v[100:103]
	v_mfma_f32_16x16x32_bf16 v[92:95], v[156:159], v[226:229], v[92:95]
	v_mfma_f32_16x16x32_bf16 v[84:87], v[166:169], v[226:229], v[84:87]
	v_mfma_f32_16x16x32_bf16 v[76:79], v[156:159], v[234:237], v[76:79]
	v_mfma_f32_16x16x32_bf16 v[68:71], v[166:169], v[234:237], v[68:71]
	s_setprio 0
	s_setprio 1
	v_mfma_f32_16x16x32_bf16 v[120:123], v[172:175], v[188:191], v[120:123]
	v_mfma_f32_16x16x32_bf16 v[112:115], v[180:183], v[188:191], v[112:115]
	v_mfma_f32_16x16x32_bf16 v[104:107], v[172:175], v[196:199], v[104:107]
	v_mfma_f32_16x16x32_bf16 v[96:99], v[180:183], v[196:199], v[96:99]
	v_mfma_f32_16x16x32_bf16 v[88:91], v[172:175], v[222:225], v[88:91]
	v_mfma_f32_16x16x32_bf16 v[80:83], v[180:183], v[222:225], v[80:83]
	v_mfma_f32_16x16x32_bf16 v[72:75], v[172:175], v[230:233], v[72:75]
	v_mfma_f32_16x16x32_bf16 v[64:67], v[180:183], v[230:233], v[64:67]
	v_mfma_f32_16x16x32_bf16 v[120:123], v[176:179], v[192:195], v[120:123]
	v_mfma_f32_16x16x32_bf16 v[112:115], v[184:187], v[192:195], v[112:115]
	v_mfma_f32_16x16x32_bf16 v[104:107], v[176:179], v[218:221], v[104:107]
	v_mfma_f32_16x16x32_bf16 v[96:99], v[184:187], v[218:221], v[96:99]
	v_mfma_f32_16x16x32_bf16 v[88:91], v[176:179], v[226:229], v[88:91]
	v_mfma_f32_16x16x32_bf16 v[80:83], v[184:187], v[226:229], v[80:83]
	v_mfma_f32_16x16x32_bf16 v[72:75], v[176:179], v[234:237], v[72:75]
	v_mfma_f32_16x16x32_bf16 v[64:67], v[184:187], v[234:237], v[64:67]
	s_setprio 0
	s_barrier
	s_add_i32 s5, s19, s80
	v_lshl_add_u64 v[238:239], s[70:71], 0, v[130:131]
	s_mov_b32 m0, s5
	ds_read_b128 v[188:191], v150 offset:16384
	ds_read_b128 v[192:195], v150 offset:17408
	ds_read_b128 v[196:199], v150 offset:18432
	ds_read_b128 v[218:221], v150 offset:19456
	ds_read_b128 v[222:225], v150 offset:20480
	ds_read_b128 v[226:229], v150 offset:21504
	ds_read_b128 v[230:233], v150 offset:22528
	ds_read_b128 v[234:237], v150 offset:23552
	global_load_lds_dwordx4 v[238:239], off
	s_add_i32 m0, s5, 0x2000
	s_add_u32 s52, s70, 0x40000
	v_lshl_add_u64 v[240:241], s[70:71], 0, v[134:135]
	s_addc_u32 s53, s71, 0
	s_add_i32 s5, s25, s80
	global_load_lds_dwordx4 v[240:241], off
	v_lshl_add_u64 v[242:243], s[52:53], 0, v[130:131]
	s_mov_b32 m0, s5
	v_lshl_add_u64 v[244:245], s[98:99], 0, v[132:133]
	global_load_lds_dwordx4 v[242:243], off
	v_lshl_add_u64 v[242:243], s[52:53], 0, v[134:135]
	s_add_i32 m0, s5, 0x2000
	s_nop 0
	global_load_lds_dwordx4 v[242:243], off
	v_lshl_add_u64 v[242:243], s[98:99], 0, v[128:129]
	s_mov_b32 m0, s81
	s_nop 0
	global_load_lds_dwordx4 v[242:243], off
	s_mov_b32 m0, s85
	s_nop 0
	global_load_lds_dwordx4 v[244:245], off
	s_waitcnt vmcnt(16)
	s_waitcnt lgkmcnt(0)
	s_barrier
	s_setprio 1
	s_waitcnt lgkmcnt(0)
	v_mfma_f32_16x16x32_bf16 v[60:63], v[152:155], v[188:191], v[60:63]
	v_mfma_f32_16x16x32_bf16 v[52:55], v[162:165], v[188:191], v[52:55]
	v_mfma_f32_16x16x32_bf16 v[44:47], v[152:155], v[196:199], v[44:47]
	v_mfma_f32_16x16x32_bf16 v[36:39], v[162:165], v[196:199], v[36:39]
	v_mfma_f32_16x16x32_bf16 v[28:31], v[152:155], v[222:225], v[28:31]
	v_mfma_f32_16x16x32_bf16 v[20:23], v[162:165], v[222:225], v[20:23]
	v_mfma_f32_16x16x32_bf16 v[12:15], v[152:155], v[230:233], v[12:15]
	v_mfma_f32_16x16x32_bf16 v[4:7], v[162:165], v[230:233], v[4:7]
	v_mfma_f32_16x16x32_bf16 v[60:63], v[156:159], v[192:195], v[60:63]
	v_mfma_f32_16x16x32_bf16 v[52:55], v[166:169], v[192:195], v[52:55]
	v_mfma_f32_16x16x32_bf16 v[44:47], v[156:159], v[218:221], v[44:47]
	v_mfma_f32_16x16x32_bf16 v[36:39], v[166:169], v[218:221], v[36:39]
	v_mfma_f32_16x16x32_bf16 v[28:31], v[156:159], v[226:229], v[28:31]
	v_mfma_f32_16x16x32_bf16 v[20:23], v[166:169], v[226:229], v[20:23]
	v_mfma_f32_16x16x32_bf16 v[12:15], v[156:159], v[234:237], v[12:15]
	v_mfma_f32_16x16x32_bf16 v[4:7], v[166:169], v[234:237], v[4:7]
	s_setprio 0
	s_setprio 1
	v_mfma_f32_16x16x32_bf16 v[56:59], v[172:175], v[188:191], v[56:59]
	v_mfma_f32_16x16x32_bf16 v[48:51], v[180:183], v[188:191], v[48:51]
	v_mfma_f32_16x16x32_bf16 v[40:43], v[172:175], v[196:199], v[40:43]
	v_mfma_f32_16x16x32_bf16 v[32:35], v[180:183], v[196:199], v[32:35]
	v_mfma_f32_16x16x32_bf16 v[24:27], v[172:175], v[222:225], v[24:27]
	v_mfma_f32_16x16x32_bf16 v[16:19], v[180:183], v[222:225], v[16:19]
	v_mfma_f32_16x16x32_bf16 v[8:11], v[172:175], v[230:233], v[8:11]
	v_mfma_f32_16x16x32_bf16 v[0:3], v[180:183], v[230:233], v[0:3]
	v_mfma_f32_16x16x32_bf16 v[56:59], v[176:179], v[192:195], v[56:59]
	v_mfma_f32_16x16x32_bf16 v[48:51], v[184:187], v[192:195], v[48:51]
	v_mfma_f32_16x16x32_bf16 v[40:43], v[176:179], v[218:221], v[40:43]
	v_mfma_f32_16x16x32_bf16 v[32:35], v[184:187], v[218:221], v[32:35]
	v_mfma_f32_16x16x32_bf16 v[24:27], v[176:179], v[226:229], v[24:27]
	v_mfma_f32_16x16x32_bf16 v[16:19], v[184:187], v[226:229], v[16:19]
	v_mfma_f32_16x16x32_bf16 v[8:11], v[176:179], v[234:237], v[8:11]
	v_mfma_f32_16x16x32_bf16 v[0:3], v[184:187], v[234:237], v[0:3]
	s_setprio 0
	s_barrier
; #define PG8_STAGE(bufoff, gbase, voff) do { _Pragma("unroll") for (int _i = 0; _i < 2; ++_i) \
;         __builtin_amdgcn_global_load_lds((const unsigned*)((const char*)(gbase) + (voff)[_i]), (PG8_LAS unsigned*)(lds + (bufoff) + ldsw + _i * 8192), 16, 0, 0); } while (0)
; #define PG8_LDA(dst, b, h) do { _Pragma("unroll") for (int m = 0; m < 4; ++m) _Pragma("unroll") for (int k = 0; k < 2; ++k) dst[m][k] = *(const PG8_LAS bf16x8*)(lds + PG8_SA(b, h) + aoff + m * 2048 + k * 1024); } while (0)
; #define PG8_LDB(dst, b, h) do { _Pragma("unroll") for (int n = 0; n < 2; ++n) _Pragma("unroll") for (int k = 0; k < 2; ++k) dst[n][k] = *(const PG8_LAS bf16x8*)(lds + PG8_SB(b, h) + boff + n * 2048 + k * 1024); } while (0)
; #define PG8_MMA(ai, bj, At, Bt) do { __builtin_amdgcn_s_setprio(1); _Pragma("unroll") for (int m = 0; m < 4; ++m) _Pragma("unroll") for (int n = 0; n < 2; ++n) _Pragma("unroll") for (int k = 0; k < 2; ++k) \
;         acc[ai][bj][m][n] = __builtin_amdgcn_mfma_f32_16x16x32_bf16(Bt[n][k], At[m][k], acc[ai][bj][m][n], 0, 0, 0); __builtin_amdgcn_s_setprio(0); } while (0)
; #define PG8_WAIT_V(n) asm volatile("s_waitcnt vmcnt(" #n ")" ::: "memory")
; #define PG8_WAIT_L(n) asm volatile("s_waitcnt lgkmcnt(" #n ")" ::: "memory")
; #define PG8_BAR __builtin_amdgcn_s_barrier()
; #define PG8_SCHED __builtin_amdgcn_sched_barrier(0)
; template <class Epi, class Sched, bool ALIGN_EPI = false, bool SP2 = false>
; __device__ __forceinline__ void gemm_phase(PG8_LAS unsigned char* lds, const Gemm g, const Sched& S, const Epi& E) {
;     ...
;             PG8_LDB(B0, 1, 0); PG8_LDB(B1, 1, 1); PG8_SCHED; PG8_LDA(At, 1, 0); PG8_STAGE(PG8_SA(0, 1), a2 + hstep, voffA);
;             PG8_WAIT_V(8); PG8_WAIT_L(0); PG8_BAR; PG8_MMA(0, 0, At, B0); PG8_MMA(0, 1, At, B1); PG8_BAR; PG8_SCHED;
	s_add_i32 s37, 0, 0x18000
	v_add_u32_e32 v151, s37, v141
	s_add_i32 s67, 0, 0x1c000
	ds_read_b128 v[152:155], v151
	ds_read_b128 v[156:159], v151 offset:1024
	ds_read_b128 v[162:165], v151 offset:2048
	ds_read_b128 v[166:169], v151 offset:3072
	v_add_u32_e32 v151, s67, v141
	ds_read_b128 v[172:175], v151
	ds_read_b128 v[176:179], v151 offset:1024
	ds_read_b128 v[180:183], v151 offset:2048
	ds_read_b128 v[184:187], v151 offset:3072
	s_add_u32 s52, s98, 0x40000
	s_addc_u32 s53, s99, 0
	s_mov_b32 m0, s93
	v_lshl_add_u64 v[246:247], s[52:53], 0, v[128:129]
	ds_read_b128 v[188:191], v150 offset:32768
	ds_read_b128 v[192:195], v150 offset:33792
	ds_read_b128 v[196:199], v150 offset:34816
	ds_read_b128 v[218:221], v150 offset:35840
	ds_read_b128 v[222:225], v150 offset:36864
	ds_read_b128 v[226:229], v150 offset:37888
	ds_read_b128 v[230:233], v150 offset:38912
	ds_read_b128 v[234:237], v150 offset:39936
	global_load_lds_dwordx4 v[246:247], off
	v_lshl_add_u64 v[246:247], s[52:53], 0, v[132:133]
	s_mov_b32 m0, s94
	s_nop 0
	global_load_lds_dwordx4 v[246:247], off
	s_waitcnt vmcnt(8)
	s_waitcnt lgkmcnt(0)
	s_barrier
	s_setprio 1
	s_waitcnt lgkmcnt(0)
	v_mfma_f32_16x16x32_bf16 v[124:127], v[152:155], v[188:191], v[124:127]
	v_mfma_f32_16x16x32_bf16 v[116:119], v[162:165], v[188:191], v[116:119]
	v_mfma_f32_16x16x32_bf16 v[108:111], v[152:155], v[196:199], v[108:111]
	v_mfma_f32_16x16x32_bf16 v[100:103], v[162:165], v[196:199], v[100:103]
	v_mfma_f32_16x16x32_bf16 v[92:95], v[152:155], v[222:225], v[92:95]
	v_mfma_f32_16x16x32_bf16 v[84:87], v[162:165], v[222:225], v[84:87]
	v_mfma_f32_16x16x32_bf16 v[76:79], v[152:155], v[230:233], v[76:79]
	v_mfma_f32_16x16x32_bf16 v[68:71], v[162:165], v[230:233], v[68:71]
	v_mfma_f32_16x16x32_bf16 v[124:127], v[156:159], v[192:195], v[124:127]
	v_mfma_f32_16x16x32_bf16 v[116:119], v[166:169], v[192:195], v[116:119]
	v_mfma_f32_16x16x32_bf16 v[108:111], v[156:159], v[218:221], v[108:111]
	v_mfma_f32_16x16x32_bf16 v[100:103], v[166:169], v[218:221], v[100:103]
	v_mfma_f32_16x16x32_bf16 v[92:95], v[156:159], v[226:229], v[92:95]
	v_mfma_f32_16x16x32_bf16 v[84:87], v[166:169], v[226:229], v[84:87]
	v_mfma_f32_16x16x32_bf16 v[76:79], v[156:159], v[234:237], v[76:79]
	v_mfma_f32_16x16x32_bf16 v[68:71], v[166:169], v[234:237], v[68:71]
	s_setprio 0
	s_setprio 1
	v_mfma_f32_16x16x32_bf16 v[120:123], v[172:175], v[188:191], v[120:123]
	v_mfma_f32_16x16x32_bf16 v[112:115], v[180:183], v[188:191], v[112:115]
	v_mfma_f32_16x16x32_bf16 v[104:107], v[172:175], v[196:199], v[104:107]
	v_mfma_f32_16x16x32_bf16 v[96:99], v[180:183], v[196:199], v[96:99]
	v_mfma_f32_16x16x32_bf16 v[88:91], v[172:175], v[222:225], v[88:91]
	v_mfma_f32_16x16x32_bf16 v[80:83], v[180:183], v[222:225], v[80:83]
	v_mfma_f32_16x16x32_bf16 v[72:75], v[172:175], v[230:233], v[72:75]
	v_mfma_f32_16x16x32_bf16 v[64:67], v[180:183], v[230:233], v[64:67]
	v_mfma_f32_16x16x32_bf16 v[120:123], v[176:179], v[192:195], v[120:123]
	v_mfma_f32_16x16x32_bf16 v[112:115], v[184:187], v[192:195], v[112:115]
	v_mfma_f32_16x16x32_bf16 v[104:107], v[176:179], v[218:221], v[104:107]
	v_mfma_f32_16x16x32_bf16 v[96:99], v[184:187], v[218:221], v[96:99]
	v_mfma_f32_16x16x32_bf16 v[88:91], v[176:179], v[226:229], v[88:91]
	v_mfma_f32_16x16x32_bf16 v[80:83], v[184:187], v[226:229], v[80:83]
	v_mfma_f32_16x16x32_bf16 v[72:75], v[176:179], v[234:237], v[72:75]
	v_mfma_f32_16x16x32_bf16 v[64:67], v[184:187], v[234:237], v[64:67]
	s_setprio 0
	s_barrier
; #define PG8_STAGE(bufoff, gbase, voff) do { _Pragma("unroll") for (int _i = 0; _i < 2; ++_i) \
;         __builtin_amdgcn_global_load_lds((const unsigned*)((const char*)(gbase) + (voff)[_i]), (PG8_LAS unsigned*)(lds + (bufoff) + ldsw + _i * 8192), 16, 0, 0); } while (0)
; #define PG8_LDA(dst, b, h) do { _Pragma("unroll") for (int m = 0; m < 4; ++m) _Pragma("unroll") for (int k = 0; k < 2; ++k) dst[m][k] = *(const PG8_LAS bf16x8*)(lds + PG8_SA(b, h) + aoff + m * 2048 + k * 1024); } while (0)
; #define PG8_MMA(ai, bj, At, Bt) do { __builtin_amdgcn_s_setprio(1); _Pragma("unroll") for (int m = 0; m < 4; ++m) _Pragma("unroll") for (int n = 0; n < 2; ++n) _Pragma("unroll") for (int k = 0; k < 2; ++k) \
;         acc[ai][bj][m][n] = __builtin_amdgcn_mfma_f32_16x16x32_bf16(Bt[n][k], At[m][k], acc[ai][bj][m][n], 0, 0, 0); __builtin_amdgcn_s_setprio(0); } while (0)
; #define PG8_WAIT_V(n) asm volatile("s_waitcnt vmcnt(" #n ")" ::: "memory")
; #define PG8_WAIT_L(n) asm volatile("s_waitcnt lgkmcnt(" #n ")" ::: "memory")
; #define PG8_BAR __builtin_amdgcn_s_barrier()
; #define PG8_SCHED __builtin_amdgcn_sched_barrier(0)
; template <class Epi, class Sched, bool ALIGN_EPI = false, bool SP2 = false>
; __device__ __forceinline__ void gemm_phase(PG8_LAS unsigned char* lds, const Gemm g, const Sched& S, const Epi& E) {
;     ...
;         for (int t = 0; t < nt; t += 2) {
;             const bool last = (t == nt - 2);
;             const char* a1 = cA + (size_t)(t + 1) * kstep;
;             const char* a2 = last ? nA : cA + (size_t)(t + 2) * kstep; const char* b2 = last ? nB : cB + (size_t)(t + 2) * kstep;
;     ...
;             PG8_LDA(At, 1, 1); PG8_STAGE(PG8_SB(1, 0), b3, voffB); PG8_STAGE(PG8_SB(1, 1), b3 + hstep, voffB); PG8_STAGE(PG8_SA(1, 0), a3, voffA);
;             PG8_WAIT_V(8); PG8_WAIT_L(0); PG8_BAR; PG8_MMA(1, 0, At, B0); PG8_MMA(1, 1, At, B1); PG8_BAR; PG8_SCHED;
	s_add_i32 s5, s37, s80
	v_lshl_add_u64 v[238:239], v[238:239], 0, s[90:91]
	s_mov_b32 m0, s5
	ds_read_b128 v[188:191], v150 offset:49152
	ds_read_b128 v[192:195], v150 offset:50176
	ds_read_b128 v[196:199], v150 offset:51200
	ds_read_b128 v[218:221], v150 offset:52224
	ds_read_b128 v[222:225], v150 offset:53248
	ds_read_b128 v[226:229], v150 offset:54272
	ds_read_b128 v[230:233], v150 offset:55296
	ds_read_b128 v[234:237], v150 offset:56320
	global_load_lds_dwordx4 v[238:239], off
	s_add_i32 m0, s5, 0x2000
	s_add_u32 s52, s70, 0x40080
	v_lshl_add_u64 v[238:239], v[240:241], 0, s[90:91]
	s_addc_u32 s53, s71, 0
	s_add_i32 s5, s67, s80
	global_load_lds_dwordx4 v[238:239], off
	v_lshl_add_u64 v[238:239], s[52:53], 0, v[130:131]
	s_mov_b32 m0, s5
	s_nop 0
	global_load_lds_dwordx4 v[238:239], off
	v_lshl_add_u64 v[238:239], s[52:53], 0, v[134:135]
	s_add_i32 m0, s5, 0x2000
	s_nop 0
	global_load_lds_dwordx4 v[238:239], off
	v_lshl_add_u64 v[238:239], v[242:243], 0, s[90:91]
	s_mov_b32 m0, s38
	s_nop 0
	global_load_lds_dwordx4 v[238:239], off
	v_lshl_add_u64 v[238:239], v[244:245], 0, s[90:91]
	s_mov_b32 m0, s39
	s_nop 0
	global_load_lds_dwordx4 v[238:239], off
	s_waitcnt vmcnt(8)
	s_waitcnt lgkmcnt(0)
	s_barrier
	s_setprio 1
	s_waitcnt lgkmcnt(0)
	v_mfma_f32_16x16x32_bf16 v[60:63], v[152:155], v[188:191], v[60:63]
	v_mfma_f32_16x16x32_bf16 v[52:55], v[162:165], v[188:191], v[52:55]
	v_mfma_f32_16x16x32_bf16 v[44:47], v[152:155], v[196:199], v[44:47]
	v_mfma_f32_16x16x32_bf16 v[36:39], v[162:165], v[196:199], v[36:39]
	v_mfma_f32_16x16x32_bf16 v[28:31], v[152:155], v[222:225], v[28:31]
	v_mfma_f32_16x16x32_bf16 v[20:23], v[162:165], v[222:225], v[20:23]
	v_mfma_f32_16x16x32_bf16 v[12:15], v[152:155], v[230:233], v[12:15]
	v_mfma_f32_16x16x32_bf16 v[4:7], v[162:165], v[230:233], v[4:7]
	v_mfma_f32_16x16x32_bf16 v[60:63], v[156:159], v[192:195], v[60:63]
	v_mfma_f32_16x16x32_bf16 v[52:55], v[166:169], v[192:195], v[52:55]
	v_mfma_f32_16x16x32_bf16 v[44:47], v[156:159], v[218:221], v[44:47]
	v_mfma_f32_16x16x32_bf16 v[36:39], v[166:169], v[218:221], v[36:39]
	v_mfma_f32_16x16x32_bf16 v[28:31], v[156:159], v[226:229], v[28:31]
	v_mfma_f32_16x16x32_bf16 v[20:23], v[166:169], v[226:229], v[20:23]
	v_mfma_f32_16x16x32_bf16 v[12:15], v[156:159], v[234:237], v[12:15]
	v_mfma_f32_16x16x32_bf16 v[4:7], v[166:169], v[234:237], v[4:7]
	s_setprio 0
	s_setprio 1
	v_mfma_f32_16x16x32_bf16 v[56:59], v[172:175], v[188:191], v[56:59]
	v_mfma_f32_16x16x32_bf16 v[48:51], v[180:183], v[188:191], v[48:51]
	v_mfma_f32_16x16x32_bf16 v[40:43], v[172:175], v[196:199], v[40:43]
	v_mfma_f32_16x16x32_bf16 v[32:35], v[180:183], v[196:199], v[32:35]
	v_mfma_f32_16x16x32_bf16 v[24:27], v[172:175], v[222:225], v[24:27]
	v_mfma_f32_16x16x32_bf16 v[16:19], v[180:183], v[222:225], v[16:19]
	v_mfma_f32_16x16x32_bf16 v[8:11], v[172:175], v[230:233], v[8:11]
	v_mfma_f32_16x16x32_bf16 v[0:3], v[180:183], v[230:233], v[0:3]
	v_mfma_f32_16x16x32_bf16 v[56:59], v[176:179], v[192:195], v[56:59]
	v_mfma_f32_16x16x32_bf16 v[48:51], v[184:187], v[192:195], v[48:51]
	v_mfma_f32_16x16x32_bf16 v[40:43], v[176:179], v[218:221], v[40:43]
	v_mfma_f32_16x16x32_bf16 v[32:35], v[184:187], v[218:221], v[32:35]
	v_mfma_f32_16x16x32_bf16 v[24:27], v[176:179], v[226:229], v[24:27]
	v_mfma_f32_16x16x32_bf16 v[16:19], v[184:187], v[226:229], v[16:19]
	v_mfma_f32_16x16x32_bf16 v[8:11], v[176:179], v[234:237], v[8:11]
	v_mfma_f32_16x16x32_bf16 v[0:3], v[184:187], v[234:237], v[0:3]
	s_setprio 0
	s_barrier
	s_add_i32 s4, s4, 2
	s_add_u32 vcc_lo, vcc_lo, 0x100
	s_addc_u32 vcc_hi, vcc_hi, 0
	s_add_u32 s46, s46, 0x100
	s_addc_u32 s47, s47, 0
	s_cmp_gt_u32 s4, 13
	s_cbranch_scc0 .LBB0_83
	s_branch .Lpeel_after_LBB083

; #define PG8_BAR __builtin_amdgcn_s_barrier()
; template <class Epi, class Sched, bool ALIGN_EPI = false, bool SP2 = false>
; __device__ __forceinline__ void gemm_phase(PG8_LAS unsigned char* lds, const Gemm g, const Sched& S, const Epi& E) {
;     ...
;         if constexpr (ALIGN_EPI) { if (wr == 0) PG8_BAR; }
.Lpeel_after_LBB083:
	s_and_b64 vcc, exec, s[64:65]
	s_cbranch_vccz .LBB0_86
	s_barrier

; #define PG8_STAGE(bufoff, gbase, voff) do { _Pragma("unroll") for (int _i = 0; _i < 2; ++_i) \
;         __builtin_amdgcn_global_load_lds((const unsigned*)((const char*)(gbase) + (voff)[_i]), (PG8_LAS unsigned*)(lds + (bufoff) + ldsw + _i * 8192), 16, 0, 0); } while (0)
; #define PG8_LDA(dst, b, h) do { _Pragma("unroll") for (int m = 0; m < 4; ++m) _Pragma("unroll") for (int k = 0; k < 2; ++k) dst[m][k] = *(const PG8_LAS bf16x8*)(lds + PG8_SA(b, h) + aoff + m * 2048 + k * 1024); } while (0)
; #define PG8_LDB(dst, b, h) do { _Pragma("unroll") for (int n = 0; n < 2; ++n) _Pragma("unroll") for (int k = 0; k < 2; ++k) dst[n][k] = *(const PG8_LAS bf16x8*)(lds + PG8_SB(b, h) + boff + n * 2048 + k * 1024); } while (0)
; #define PG8_WAIT_V(n) asm volatile("s_waitcnt vmcnt(" #n ")" ::: "memory")
; #define PG8_WAIT_L(n) asm volatile("s_waitcnt lgkmcnt(" #n ")" ::: "memory")
; #define PG8_BAR __builtin_amdgcn_s_barrier()
; #define PG8_SCHED __builtin_amdgcn_sched_barrier(0)
; template <class Epi, class Sched, bool ALIGN_EPI = false, bool SP2 = false>
; __device__ __forceinline__ void gemm_phase(PG8_LAS unsigned char* lds, const Gemm g, const Sched& S, const Epi& E) {
;     ...
;         const bool has_next = S.next(ui + 1, nxt);
;         const char* nA = has_next ? (const char*)g.A + (size_t)nxt.pm * tstep : cA; const char* nB = has_next ? (const char*)g.Bt + (size_t)nxt.pn * tstep : cB;
;         for (int t = 0; t < nt; t += 2) {
;             const bool last = (t == nt - 2);
;             const char* a1 = cA + (size_t)(t + 1) * kstep;
;             const char* a2 = last ? nA : cA + (size_t)(t + 2) * kstep; const char* b2 = last ? nB : cB + (size_t)(t + 2) * kstep;
;             const char* a3 = a2 + kstep; const char* b3 = b2 + kstep;
;             if (last && has_next) S.a_ready(nxt);
;             if constexpr (SP2) {
;             PG8_LDB(B0, 0, 0); PG8_LDB(B1, 0, 1); PG8_SCHED; PG8_LDA(At, 0, 0); PG8_STAGE(PG8_SA(1, 1), a1 + hstep, voffA);
;             PG8_WAIT_V(8); PG8_WAIT_L(0); PG8_BAR; PG8_MMA(0, 0, At, B0); PG8_MMA(0, 1, At, B1); PG8_BAR; PG8_SCHED;
;     ...
;         for (int a = 0; a < 2; ++a)
; #pragma unroll
;             for (int b = 0; b < 2; ++b)
; #pragma unroll
;                 for (int m = 0; m < 4; ++m)
; #pragma unroll
;                     for (int n = 0; n < 2; ++n) acc[a][b][m][n] = (f32x4){0.f, 0.f, 0.f, 0.f};
;         cur = nxt; cA = nA; cB = nB; ++ui;
.LBB0_120:
	v_readlane_b32 s4, v255, 19
	s_ashr_i32 s46, s68, 4
	v_readlane_b32 s5, v255, 20
	s_add_i32 s46, s68, s46
	s_and_b64 s[4:5], s[4:5], s[8:9]
	s_add_i32 s46, s46, 1
	s_and_b64 s[4:5], s[4:5], exec
	s_cselect_b32 s68, s46, s68
	s_ashr_i32 s69, s68, 31
	s_lshl_b64 s[4:5], s[68:69], 19
	s_add_u32 s70, s60, s4
	s_addc_u32 s71, s61, s5
	s_and_b64 s[4:5], s[8:9], exec
	s_cselect_b32 s69, s71, s51
	s_cselect_b32 s94, s70, s50
	s_ashr_i32 s67, s66, 31
	s_lshl_b64 s[4:5], s[66:67], 19
	s_add_u32 s86, s3, s4
	s_addc_u32 s87, s13, s5
	s_and_b64 s[4:5], s[8:9], exec
	s_cselect_b32 s67, s87, s27
	s_cselect_b32 vcc_lo, s86, s26
	s_add_u32 s98, s50, 0x40080
	s_addc_u32 s99, s51, 0
	s_add_u32 s46, s26, 0x100
	v_mov_b32_e32 v0, 0
	s_addc_u32 s47, s27, 0
	s_mov_b32 vcc_hi, -2
	v_mov_b32_e32 v1, v0
	v_mov_b32_e32 v2, v0
	v_mov_b32_e32 v3, v0
	v_mov_b32_e32 v8, v0
	v_mov_b32_e32 v9, v0
	v_mov_b32_e32 v10, v0
	v_mov_b32_e32 v11, v0
	v_mov_b32_e32 v16, v0
	v_mov_b32_e32 v17, v0
	v_mov_b32_e32 v18, v0
	v_mov_b32_e32 v19, v0
	v_mov_b32_e32 v24, v0
	v_mov_b32_e32 v25, v0
	v_mov_b32_e32 v26, v0
	v_mov_b32_e32 v27, v0
	v_mov_b32_e32 v32, v0
	v_mov_b32_e32 v33, v0
	v_mov_b32_e32 v34, v0
	v_mov_b32_e32 v35, v0
	v_mov_b32_e32 v40, v0
	v_mov_b32_e32 v41, v0
	v_mov_b32_e32 v42, v0
	v_mov_b32_e32 v43, v0
	v_mov_b32_e32 v48, v0
	v_mov_b32_e32 v49, v0
	v_mov_b32_e32 v50, v0
	v_mov_b32_e32 v51, v0
	v_mov_b32_e32 v56, v0
	v_mov_b32_e32 v57, v0
	v_mov_b32_e32 v58, v0
	v_mov_b32_e32 v59, v0
	v_mov_b32_e32 v4, v0
	v_mov_b32_e32 v5, v0
	v_mov_b32_e32 v6, v0
	v_mov_b32_e32 v7, v0
	v_mov_b32_e32 v12, v0
	v_mov_b32_e32 v13, v0
	v_mov_b32_e32 v14, v0
	v_mov_b32_e32 v15, v0
	v_mov_b32_e32 v20, v0
	v_mov_b32_e32 v21, v0
	v_mov_b32_e32 v22, v0
	v_mov_b32_e32 v23, v0
	v_mov_b32_e32 v28, v0
	v_mov_b32_e32 v29, v0
	v_mov_b32_e32 v30, v0
	v_mov_b32_e32 v31, v0
	v_mov_b32_e32 v36, v0
	v_mov_b32_e32 v37, v0
	v_mov_b32_e32 v38, v0
	v_mov_b32_e32 v39, v0
	v_mov_b32_e32 v44, v0
	v_mov_b32_e32 v45, v0
	v_mov_b32_e32 v46, v0
	v_mov_b32_e32 v47, v0
	v_mov_b32_e32 v52, v0
	v_mov_b32_e32 v53, v0
	v_mov_b32_e32 v54, v0
	v_mov_b32_e32 v55, v0
	v_mov_b32_e32 v60, v0
	v_mov_b32_e32 v61, v0
	v_mov_b32_e32 v62, v0
	v_mov_b32_e32 v63, v0
	v_mov_b32_e32 v64, v0
	v_mov_b32_e32 v65, v0
	v_mov_b32_e32 v66, v0
	v_mov_b32_e32 v67, v0
	v_mov_b32_e32 v72, v0
	v_mov_b32_e32 v73, v0
	v_mov_b32_e32 v74, v0
	v_mov_b32_e32 v75, v0
	v_mov_b32_e32 v80, v0
	v_mov_b32_e32 v81, v0
	v_mov_b32_e32 v82, v0
	v_mov_b32_e32 v83, v0
	v_mov_b32_e32 v88, v0
	v_mov_b32_e32 v89, v0
	v_mov_b32_e32 v90, v0
	v_mov_b32_e32 v91, v0
	v_mov_b32_e32 v96, v0
	v_mov_b32_e32 v97, v0
	v_mov_b32_e32 v98, v0
	v_mov_b32_e32 v99, v0
	v_mov_b32_e32 v104, v0
	v_mov_b32_e32 v105, v0
	v_mov_b32_e32 v106, v0
	v_mov_b32_e32 v107, v0
	v_mov_b32_e32 v112, v0
	v_mov_b32_e32 v113, v0
	v_mov_b32_e32 v114, v0
	v_mov_b32_e32 v115, v0
	v_mov_b32_e32 v120, v0
	v_mov_b32_e32 v121, v0
	v_mov_b32_e32 v122, v0
	v_mov_b32_e32 v123, v0
	v_mov_b32_e32 v68, v0
	v_mov_b32_e32 v69, v0
	v_mov_b32_e32 v70, v0
	v_mov_b32_e32 v71, v0
	v_mov_b32_e32 v76, v0
	v_mov_b32_e32 v77, v0
	v_mov_b32_e32 v78, v0
	v_mov_b32_e32 v79, v0
	v_mov_b32_e32 v84, v0
	v_mov_b32_e32 v85, v0
	v_mov_b32_e32 v86, v0
	v_mov_b32_e32 v87, v0
	v_mov_b32_e32 v92, v0
	v_mov_b32_e32 v93, v0
	v_mov_b32_e32 v94, v0
	v_mov_b32_e32 v95, v0
	v_mov_b32_e32 v100, v0
	v_mov_b32_e32 v101, v0
	v_mov_b32_e32 v102, v0
	v_mov_b32_e32 v103, v0
	v_mov_b32_e32 v108, v0
	v_mov_b32_e32 v109, v0
	v_mov_b32_e32 v110, v0
	v_mov_b32_e32 v111, v0
	v_mov_b32_e32 v116, v0
	v_mov_b32_e32 v117, v0
	v_mov_b32_e32 v118, v0
	v_mov_b32_e32 v119, v0
	v_mov_b32_e32 v124, v0
	v_mov_b32_e32 v125, v0
	v_mov_b32_e32 v126, v0
	v_mov_b32_e32 v127, v0
	s_cmp_eq_u32 s93, 1
	s_cbranch_scc1 .LBB0_121
	s_add_u32 s4, s98, 0xfffc0080
	s_addc_u32 s5, s99, -1
	s_add_i32 s52, 0, 0x10000
	s_cmp_eq_u32 vcc_hi, 12
	s_cselect_b32 s51, s69, s5
	s_cselect_b32 s50, s94, s4
	v_add_u32_e32 v151, s52, v141
	s_cselect_b32 s27, s67, s47
	s_cselect_b32 s26, vcc_lo, s46
	s_add_i32 s53, 0, 0x14000
	ds_read_b128 v[152:155], v151
	ds_read_b128 v[156:159], v151 offset:1024
	ds_read_b128 v[162:165], v151 offset:2048
	ds_read_b128 v[166:169], v151 offset:3072
	v_add_u32_e32 v151, s53, v141
	ds_read_b128 v[172:175], v151
	ds_read_b128 v[176:179], v151 offset:1024
	ds_read_b128 v[180:183], v151 offset:2048
	ds_read_b128 v[184:187], v151 offset:3072
	v_lshl_add_u64 v[238:239], s[98:99], 0, v[136:137]
	s_add_i32 m0, s38, 0xc000
	ds_read_b128 v[188:191], v150
	ds_read_b128 v[192:195], v150 offset:1024
	ds_read_b128 v[196:199], v150 offset:2048
	ds_read_b128 v[218:221], v150 offset:3072
	ds_read_b128 v[222:225], v150 offset:4096
	ds_read_b128 v[226:229], v150 offset:5120
	ds_read_b128 v[230:233], v150 offset:6144
	ds_read_b128 v[234:237], v150 offset:7168
	global_load_lds_dwordx4 v[238:239], off
	v_lshl_add_u64 v[238:239], s[98:99], 0, v[138:139]
	s_add_i32 m0, s38, 0xe000
	s_nop 0
	global_load_lds_dwordx4 v[238:239], off
	s_waitcnt vmcnt(16)
	s_waitcnt lgkmcnt(0)
	s_barrier
; #define PG8_STAGE(bufoff, gbase, voff) do { _Pragma("unroll") for (int _i = 0; _i < 2; ++_i) \
;         __builtin_amdgcn_global_load_lds((const unsigned*)((const char*)(gbase) + (voff)[_i]), (PG8_LAS unsigned*)(lds + (bufoff) + ldsw + _i * 8192), 16, 0, 0); } while (0)
; #define PG8_LDA(dst, b, h) do { _Pragma("unroll") for (int m = 0; m < 4; ++m) _Pragma("unroll") for (int k = 0; k < 2; ++k) dst[m][k] = *(const PG8_LAS bf16x8*)(lds + PG8_SA(b, h) + aoff + m * 2048 + k * 1024); } while (0)
; #define PG8_LDB(dst, b, h) do { _Pragma("unroll") for (int n = 0; n < 2; ++n) _Pragma("unroll") for (int k = 0; k < 2; ++k) dst[n][k] = *(const PG8_LAS bf16x8*)(lds + PG8_SB(b, h) + boff + n * 2048 + k * 1024); } while (0)
; #define PG8_MMA(ai, bj, At, Bt) do { __builtin_amdgcn_s_setprio(1); _Pragma("unroll") for (int m = 0; m < 4; ++m) _Pragma("unroll") for (int n = 0; n < 2; ++n) _Pragma("unroll") for (int k = 0; k < 2; ++k) \
;         acc[ai][bj][m][n] = __builtin_amdgcn_mfma_f32_16x16x32_bf16(Bt[n][k], At[m][k], acc[ai][bj][m][n], 0, 0, 0); __builtin_amdgcn_s_setprio(0); } while (0)
; #define PG8_WAIT_V(n) asm volatile("s_waitcnt vmcnt(" #n ")" ::: "memory")
; #define PG8_WAIT_L(n) asm volatile("s_waitcnt lgkmcnt(" #n ")" ::: "memory")
; #define PG8_BAR __builtin_amdgcn_s_barrier()
; #define PG8_SCHED __builtin_amdgcn_sched_barrier(0)
; template <class Epi, class Sched, bool ALIGN_EPI = false, bool SP2 = false>
; __device__ __forceinline__ void gemm_phase(PG8_LAS unsigned char* lds, const Gemm g, const Sched& S, const Epi& E) {
;     ...
;             PG8_LDB(B0, 0, 0); PG8_LDB(B1, 0, 1); PG8_SCHED; PG8_LDA(At, 0, 0); PG8_STAGE(PG8_SA(1, 1), a1 + hstep, voffA);
;             PG8_WAIT_V(8); PG8_WAIT_L(0); PG8_BAR; PG8_MMA(0, 0, At, B0); PG8_MMA(0, 1, At, B1); PG8_BAR; PG8_SCHED;
;             PG8_LDA(At, 0, 1); PG8_STAGE(PG8_SB(0, 0), b2, voffB); PG8_STAGE(PG8_SB(0, 1), b2 + hstep, voffB); PG8_STAGE(PG8_SA(0, 0), a2, voffA);
;             PG8_WAIT_V(8); PG8_WAIT_L(0); PG8_BAR; PG8_MMA(1, 0, At, B0); PG8_MMA(1, 1, At, B1); PG8_BAR; PG8_SCHED;
	s_setprio 1
	s_waitcnt lgkmcnt(0)
	v_mfma_f32_16x16x32_bf16 v[124:127], v[152:155], v[188:191], v[124:127]
	v_mfma_f32_16x16x32_bf16 v[116:119], v[162:165], v[188:191], v[116:119]
	v_mfma_f32_16x16x32_bf16 v[108:111], v[152:155], v[196:199], v[108:111]
	v_mfma_f32_16x16x32_bf16 v[100:103], v[162:165], v[196:199], v[100:103]
	v_mfma_f32_16x16x32_bf16 v[92:95], v[152:155], v[222:225], v[92:95]
	v_mfma_f32_16x16x32_bf16 v[84:87], v[162:165], v[222:225], v[84:87]
	v_mfma_f32_16x16x32_bf16 v[76:79], v[152:155], v[230:233], v[76:79]
	v_mfma_f32_16x16x32_bf16 v[68:71], v[162:165], v[230:233], v[68:71]
	v_mfma_f32_16x16x32_bf16 v[124:127], v[156:159], v[192:195], v[124:127]
	v_mfma_f32_16x16x32_bf16 v[116:119], v[166:169], v[192:195], v[116:119]
	v_mfma_f32_16x16x32_bf16 v[108:111], v[156:159], v[218:221], v[108:111]
	v_mfma_f32_16x16x32_bf16 v[100:103], v[166:169], v[218:221], v[100:103]
	v_mfma_f32_16x16x32_bf16 v[92:95], v[156:159], v[226:229], v[92:95]
	v_mfma_f32_16x16x32_bf16 v[84:87], v[166:169], v[226:229], v[84:87]
	v_mfma_f32_16x16x32_bf16 v[76:79], v[156:159], v[234:237], v[76:79]
	v_mfma_f32_16x16x32_bf16 v[68:71], v[166:169], v[234:237], v[68:71]
	s_setprio 0
	s_setprio 1
	v_mfma_f32_16x16x32_bf16 v[120:123], v[172:175], v[188:191], v[120:123]
	v_mfma_f32_16x16x32_bf16 v[112:115], v[180:183], v[188:191], v[112:115]
	v_mfma_f32_16x16x32_bf16 v[104:107], v[172:175], v[196:199], v[104:107]
	v_mfma_f32_16x16x32_bf16 v[96:99], v[180:183], v[196:199], v[96:99]
	v_mfma_f32_16x16x32_bf16 v[88:91], v[172:175], v[222:225], v[88:91]
	v_mfma_f32_16x16x32_bf16 v[80:83], v[180:183], v[222:225], v[80:83]
	v_mfma_f32_16x16x32_bf16 v[72:75], v[172:175], v[230:233], v[72:75]
	v_mfma_f32_16x16x32_bf16 v[64:67], v[180:183], v[230:233], v[64:67]
	v_mfma_f32_16x16x32_bf16 v[120:123], v[176:179], v[192:195], v[120:123]
	v_mfma_f32_16x16x32_bf16 v[112:115], v[184:187], v[192:195], v[112:115]
	v_mfma_f32_16x16x32_bf16 v[104:107], v[176:179], v[218:221], v[104:107]
	v_mfma_f32_16x16x32_bf16 v[96:99], v[184:187], v[218:221], v[96:99]
	v_mfma_f32_16x16x32_bf16 v[88:91], v[176:179], v[226:229], v[88:91]
	v_mfma_f32_16x16x32_bf16 v[80:83], v[184:187], v[226:229], v[80:83]
	v_mfma_f32_16x16x32_bf16 v[72:75], v[176:179], v[234:237], v[72:75]
	v_mfma_f32_16x16x32_bf16 v[64:67], v[184:187], v[234:237], v[64:67]
	s_setprio 0
	s_barrier
	s_add_i32 s4, s52, s25
	v_lshl_add_u64 v[238:239], s[26:27], 0, v[132:133]
	s_mov_b32 m0, s4
	ds_read_b128 v[188:191], v150 offset:16384
	ds_read_b128 v[192:195], v150 offset:17408
	ds_read_b128 v[196:199], v150 offset:18432
	ds_read_b128 v[218:221], v150 offset:19456
	ds_read_b128 v[222:225], v150 offset:20480
	ds_read_b128 v[226:229], v150 offset:21504
	ds_read_b128 v[230:233], v150 offset:22528
	ds_read_b128 v[234:237], v150 offset:23552
	global_load_lds_dwordx4 v[238:239], off
	s_add_i32 m0, s4, 0x2000
	s_add_u32 s4, s26, 0x40000
	v_lshl_add_u64 v[240:241], s[26:27], 0, v[128:129]
	s_addc_u32 s5, s27, 0
	s_add_i32 s52, s53, s25
	global_load_lds_dwordx4 v[240:241], off
	v_lshl_add_u64 v[242:243], s[4:5], 0, v[132:133]
	s_mov_b32 m0, s52
	v_lshl_add_u64 v[244:245], s[50:51], 0, v[130:131]
	global_load_lds_dwordx4 v[242:243], off
	v_lshl_add_u64 v[242:243], s[4:5], 0, v[128:129]
	s_add_i32 m0, s52, 0x2000
	s_nop 0
	global_load_lds_dwordx4 v[242:243], off
	v_lshl_add_u64 v[242:243], s[50:51], 0, v[134:135]
	s_mov_b32 m0, s38
	s_nop 0
	global_load_lds_dwordx4 v[242:243], off
	s_mov_b32 m0, s39
	s_nop 0
	global_load_lds_dwordx4 v[244:245], off
	s_waitcnt vmcnt(16)
	s_waitcnt lgkmcnt(0)
	s_barrier
	s_setprio 1
	s_waitcnt lgkmcnt(0)
	v_mfma_f32_16x16x32_bf16 v[60:63], v[152:155], v[188:191], v[60:63]
	v_mfma_f32_16x16x32_bf16 v[52:55], v[162:165], v[188:191], v[52:55]
	v_mfma_f32_16x16x32_bf16 v[44:47], v[152:155], v[196:199], v[44:47]
	v_mfma_f32_16x16x32_bf16 v[36:39], v[162:165], v[196:199], v[36:39]
	v_mfma_f32_16x16x32_bf16 v[28:31], v[152:155], v[222:225], v[28:31]
	v_mfma_f32_16x16x32_bf16 v[20:23], v[162:165], v[222:225], v[20:23]
	v_mfma_f32_16x16x32_bf16 v[12:15], v[152:155], v[230:233], v[12:15]
	v_mfma_f32_16x16x32_bf16 v[4:7], v[162:165], v[230:233], v[4:7]
	v_mfma_f32_16x16x32_bf16 v[60:63], v[156:159], v[192:195], v[60:63]
	v_mfma_f32_16x16x32_bf16 v[52:55], v[166:169], v[192:195], v[52:55]
	v_mfma_f32_16x16x32_bf16 v[44:47], v[156:159], v[218:221], v[44:47]
	v_mfma_f32_16x16x32_bf16 v[36:39], v[166:169], v[218:221], v[36:39]
	v_mfma_f32_16x16x32_bf16 v[28:31], v[156:159], v[226:229], v[28:31]
	v_mfma_f32_16x16x32_bf16 v[20:23], v[166:169], v[226:229], v[20:23]
	v_mfma_f32_16x16x32_bf16 v[12:15], v[156:159], v[234:237], v[12:15]
	v_mfma_f32_16x16x32_bf16 v[4:7], v[166:169], v[234:237], v[4:7]
	s_setprio 0
	s_setprio 1
	v_mfma_f32_16x16x32_bf16 v[56:59], v[172:175], v[188:191], v[56:59]
	v_mfma_f32_16x16x32_bf16 v[48:51], v[180:183], v[188:191], v[48:51]
	v_mfma_f32_16x16x32_bf16 v[40:43], v[172:175], v[196:199], v[40:43]
	v_mfma_f32_16x16x32_bf16 v[32:35], v[180:183], v[196:199], v[32:35]
	v_mfma_f32_16x16x32_bf16 v[24:27], v[172:175], v[222:225], v[24:27]
	v_mfma_f32_16x16x32_bf16 v[16:19], v[180:183], v[222:225], v[16:19]
	v_mfma_f32_16x16x32_bf16 v[8:11], v[172:175], v[230:233], v[8:11]
	v_mfma_f32_16x16x32_bf16 v[0:3], v[180:183], v[230:233], v[0:3]
	v_mfma_f32_16x16x32_bf16 v[56:59], v[176:179], v[192:195], v[56:59]
	v_mfma_f32_16x16x32_bf16 v[48:51], v[184:187], v[192:195], v[48:51]
	v_mfma_f32_16x16x32_bf16 v[40:43], v[176:179], v[218:221], v[40:43]
	v_mfma_f32_16x16x32_bf16 v[32:35], v[184:187], v[218:221], v[32:35]
	v_mfma_f32_16x16x32_bf16 v[24:27], v[176:179], v[226:229], v[24:27]
	v_mfma_f32_16x16x32_bf16 v[16:19], v[184:187], v[226:229], v[16:19]
	v_mfma_f32_16x16x32_bf16 v[8:11], v[176:179], v[234:237], v[8:11]
	v_mfma_f32_16x16x32_bf16 v[0:3], v[184:187], v[234:237], v[0:3]
	s_setprio 0
	s_barrier
; #define PG8_STAGE(bufoff, gbase, voff) do { _Pragma("unroll") for (int _i = 0; _i < 2; ++_i) \
;         __builtin_amdgcn_global_load_lds((const unsigned*)((const char*)(gbase) + (voff)[_i]), (PG8_LAS unsigned*)(lds + (bufoff) + ldsw + _i * 8192), 16, 0, 0); } while (0)
; #define PG8_LDA(dst, b, h) do { _Pragma("unroll") for (int m = 0; m < 4; ++m) _Pragma("unroll") for (int k = 0; k < 2; ++k) dst[m][k] = *(const PG8_LAS bf16x8*)(lds + PG8_SA(b, h) + aoff + m * 2048 + k * 1024); } while (0)
; #define PG8_LDB(dst, b, h) do { _Pragma("unroll") for (int n = 0; n < 2; ++n) _Pragma("unroll") for (int k = 0; k < 2; ++k) dst[n][k] = *(const PG8_LAS bf16x8*)(lds + PG8_SB(b, h) + boff + n * 2048 + k * 1024); } while (0)
; #define PG8_MMA(ai, bj, At, Bt) do { __builtin_amdgcn_s_setprio(1); _Pragma("unroll") for (int m = 0; m < 4; ++m) _Pragma("unroll") for (int n = 0; n < 2; ++n) _Pragma("unroll") for (int k = 0; k < 2; ++k) \
;         acc[ai][bj][m][n] = __builtin_amdgcn_mfma_f32_16x16x32_bf16(Bt[n][k], At[m][k], acc[ai][bj][m][n], 0, 0, 0); __builtin_amdgcn_s_setprio(0); } while (0)
; #define PG8_WAIT_V(n) asm volatile("s_waitcnt vmcnt(" #n ")" ::: "memory")
; #define PG8_WAIT_L(n) asm volatile("s_waitcnt lgkmcnt(" #n ")" ::: "memory")
; #define PG8_BAR __builtin_amdgcn_s_barrier()
; #define PG8_SCHED __builtin_amdgcn_sched_barrier(0)
; template <class Epi, class Sched, bool ALIGN_EPI = false, bool SP2 = false>
; __device__ __forceinline__ void gemm_phase(PG8_LAS unsigned char* lds, const Gemm g, const Sched& S, const Epi& E) {
;     ...
;             PG8_LDB(B0, 1, 0); PG8_LDB(B1, 1, 1); PG8_SCHED; PG8_LDA(At, 1, 0); PG8_STAGE(PG8_SA(0, 1), a2 + hstep, voffA);
;             PG8_WAIT_V(8); PG8_WAIT_L(0); PG8_BAR; PG8_MMA(0, 0, At, B0); PG8_MMA(0, 1, At, B1); PG8_BAR; PG8_SCHED;
	s_add_i32 s52, 0, 0x18000
	v_add_u32_e32 v151, s52, v141
	s_add_i32 s53, 0, 0x1c000
	ds_read_b128 v[152:155], v151
	ds_read_b128 v[156:159], v151 offset:1024
	ds_read_b128 v[162:165], v151 offset:2048
	ds_read_b128 v[166:169], v151 offset:3072
	v_add_u32_e32 v151, s53, v141
	ds_read_b128 v[172:175], v151
	ds_read_b128 v[176:179], v151 offset:1024
	ds_read_b128 v[180:183], v151 offset:2048
	ds_read_b128 v[184:187], v151 offset:3072
	s_add_u32 s4, s50, 0x40000
	s_addc_u32 s5, s51, 0
	s_mov_b32 m0, s81
	v_lshl_add_u64 v[246:247], s[4:5], 0, v[134:135]
	ds_read_b128 v[188:191], v150 offset:32768
	ds_read_b128 v[192:195], v150 offset:33792
	ds_read_b128 v[196:199], v150 offset:34816
	ds_read_b128 v[218:221], v150 offset:35840
	ds_read_b128 v[222:225], v150 offset:36864
	ds_read_b128 v[226:229], v150 offset:37888
	ds_read_b128 v[230:233], v150 offset:38912
	ds_read_b128 v[234:237], v150 offset:39936
	global_load_lds_dwordx4 v[246:247], off
	v_lshl_add_u64 v[246:247], s[4:5], 0, v[130:131]
	s_mov_b32 m0, s85
	s_nop 0
	global_load_lds_dwordx4 v[246:247], off
	s_waitcnt vmcnt(8)
	s_waitcnt lgkmcnt(0)
	s_barrier
	s_setprio 1
	s_waitcnt lgkmcnt(0)
	v_mfma_f32_16x16x32_bf16 v[124:127], v[152:155], v[188:191], v[124:127]
	v_mfma_f32_16x16x32_bf16 v[116:119], v[162:165], v[188:191], v[116:119]
	v_mfma_f32_16x16x32_bf16 v[108:111], v[152:155], v[196:199], v[108:111]
	v_mfma_f32_16x16x32_bf16 v[100:103], v[162:165], v[196:199], v[100:103]
	v_mfma_f32_16x16x32_bf16 v[92:95], v[152:155], v[222:225], v[92:95]
	v_mfma_f32_16x16x32_bf16 v[84:87], v[162:165], v[222:225], v[84:87]
	v_mfma_f32_16x16x32_bf16 v[76:79], v[152:155], v[230:233], v[76:79]
	v_mfma_f32_16x16x32_bf16 v[68:71], v[162:165], v[230:233], v[68:71]
	v_mfma_f32_16x16x32_bf16 v[124:127], v[156:159], v[192:195], v[124:127]
	v_mfma_f32_16x16x32_bf16 v[116:119], v[166:169], v[192:195], v[116:119]
	v_mfma_f32_16x16x32_bf16 v[108:111], v[156:159], v[218:221], v[108:111]
	v_mfma_f32_16x16x32_bf16 v[100:103], v[166:169], v[218:221], v[100:103]
	v_mfma_f32_16x16x32_bf16 v[92:95], v[156:159], v[226:229], v[92:95]
	v_mfma_f32_16x16x32_bf16 v[84:87], v[166:169], v[226:229], v[84:87]
	v_mfma_f32_16x16x32_bf16 v[76:79], v[156:159], v[234:237], v[76:79]
	v_mfma_f32_16x16x32_bf16 v[68:71], v[166:169], v[234:237], v[68:71]
	s_setprio 0
	s_setprio 1
	v_mfma_f32_16x16x32_bf16 v[120:123], v[172:175], v[188:191], v[120:123]
	v_mfma_f32_16x16x32_bf16 v[112:115], v[180:183], v[188:191], v[112:115]
	v_mfma_f32_16x16x32_bf16 v[104:107], v[172:175], v[196:199], v[104:107]
	v_mfma_f32_16x16x32_bf16 v[96:99], v[180:183], v[196:199], v[96:99]
	v_mfma_f32_16x16x32_bf16 v[88:91], v[172:175], v[222:225], v[88:91]
	v_mfma_f32_16x16x32_bf16 v[80:83], v[180:183], v[222:225], v[80:83]
	v_mfma_f32_16x16x32_bf16 v[72:75], v[172:175], v[230:233], v[72:75]
	v_mfma_f32_16x16x32_bf16 v[64:67], v[180:183], v[230:233], v[64:67]
	v_mfma_f32_16x16x32_bf16 v[120:123], v[176:179], v[192:195], v[120:123]
	v_mfma_f32_16x16x32_bf16 v[112:115], v[184:187], v[192:195], v[112:115]
	v_mfma_f32_16x16x32_bf16 v[104:107], v[176:179], v[218:221], v[104:107]
	v_mfma_f32_16x16x32_bf16 v[96:99], v[184:187], v[218:221], v[96:99]
	v_mfma_f32_16x16x32_bf16 v[88:91], v[176:179], v[226:229], v[88:91]
	v_mfma_f32_16x16x32_bf16 v[80:83], v[184:187], v[226:229], v[80:83]
	v_mfma_f32_16x16x32_bf16 v[72:75], v[176:179], v[234:237], v[72:75]
	v_mfma_f32_16x16x32_bf16 v[64:67], v[184:187], v[234:237], v[64:67]
	s_setprio 0
	s_barrier
; #define PG8_STAGE(bufoff, gbase, voff) do { _Pragma("unroll") for (int _i = 0; _i < 2; ++_i) \
;         __builtin_amdgcn_global_load_lds((const unsigned*)((const char*)(gbase) + (voff)[_i]), (PG8_LAS unsigned*)(lds + (bufoff) + ldsw + _i * 8192), 16, 0, 0); } while (0)
; #define PG8_LDA(dst, b, h) do { _Pragma("unroll") for (int m = 0; m < 4; ++m) _Pragma("unroll") for (int k = 0; k < 2; ++k) dst[m][k] = *(const PG8_LAS bf16x8*)(lds + PG8_SA(b, h) + aoff + m * 2048 + k * 1024); } while (0)
; #define PG8_MMA(ai, bj, At, Bt) do { __builtin_amdgcn_s_setprio(1); _Pragma("unroll") for (int m = 0; m < 4; ++m) _Pragma("unroll") for (int n = 0; n < 2; ++n) _Pragma("unroll") for (int k = 0; k < 2; ++k) \
;         acc[ai][bj][m][n] = __builtin_amdgcn_mfma_f32_16x16x32_bf16(Bt[n][k], At[m][k], acc[ai][bj][m][n], 0, 0, 0); __builtin_amdgcn_s_setprio(0); } while (0)
; #define PG8_WAIT_V(n) asm volatile("s_waitcnt vmcnt(" #n ")" ::: "memory")
; #define PG8_WAIT_L(n) asm volatile("s_waitcnt lgkmcnt(" #n ")" ::: "memory")
; #define PG8_BAR __builtin_amdgcn_s_barrier()
; #define PG8_SCHED __builtin_amdgcn_sched_barrier(0)
; template <class Epi, class Sched, bool ALIGN_EPI = false, bool SP2 = false>
; __device__ __forceinline__ void gemm_phase(PG8_LAS unsigned char* lds, const Gemm g, const Sched& S, const Epi& E) {
;     ...
;         for (int t = 0; t < nt; t += 2) {
;             const bool last = (t == nt - 2);
;             const char* a1 = cA + (size_t)(t + 1) * kstep;
;             const char* a2 = last ? nA : cA + (size_t)(t + 2) * kstep; const char* b2 = last ? nB : cB + (size_t)(t + 2) * kstep;
;     ...
;             PG8_LDA(At, 1, 1); PG8_STAGE(PG8_SB(1, 0), b3, voffB); PG8_STAGE(PG8_SB(1, 1), b3 + hstep, voffB); PG8_STAGE(PG8_SA(1, 0), a3, voffA);
;             PG8_WAIT_V(8); PG8_WAIT_L(0); PG8_BAR; PG8_MMA(1, 0, At, B0); PG8_MMA(1, 1, At, B1); PG8_BAR; PG8_SCHED;
	s_add_i32 s4, s52, s25
	v_lshl_add_u64 v[238:239], v[238:239], 0, s[90:91]
	s_mov_b32 m0, s4
	ds_read_b128 v[188:191], v150 offset:49152
	ds_read_b128 v[192:195], v150 offset:50176
	ds_read_b128 v[196:199], v150 offset:51200
	ds_read_b128 v[218:221], v150 offset:52224
	ds_read_b128 v[222:225], v150 offset:53248
	ds_read_b128 v[226:229], v150 offset:54272
	ds_read_b128 v[230:233], v150 offset:55296
	ds_read_b128 v[234:237], v150 offset:56320
	global_load_lds_dwordx4 v[238:239], off
	s_add_i32 m0, s4, 0x2000
	s_add_u32 s4, s26, 0x40080
	v_lshl_add_u64 v[238:239], v[240:241], 0, s[90:91]
	s_addc_u32 s5, s27, 0
	s_add_i32 s26, s53, s25
	global_load_lds_dwordx4 v[238:239], off
	v_lshl_add_u64 v[238:239], s[4:5], 0, v[132:133]
	s_mov_b32 m0, s26
	s_nop 0
	global_load_lds_dwordx4 v[238:239], off
	v_lshl_add_u64 v[238:239], s[4:5], 0, v[128:129]
	s_add_i32 m0, s26, 0x2000
	s_nop 0
	global_load_lds_dwordx4 v[238:239], off
	v_lshl_add_u64 v[238:239], v[242:243], 0, s[90:91]
	s_mov_b32 m0, s22
	s_nop 0
	global_load_lds_dwordx4 v[238:239], off
	v_lshl_add_u64 v[238:239], v[244:245], 0, s[90:91]
	s_mov_b32 m0, s23
	s_nop 0
	global_load_lds_dwordx4 v[238:239], off
	s_waitcnt vmcnt(8)
	s_waitcnt lgkmcnt(0)
	s_barrier
	s_setprio 1
	s_waitcnt lgkmcnt(0)
	v_mfma_f32_16x16x32_bf16 v[60:63], v[152:155], v[188:191], v[60:63]
	v_mfma_f32_16x16x32_bf16 v[52:55], v[162:165], v[188:191], v[52:55]
	v_mfma_f32_16x16x32_bf16 v[44:47], v[152:155], v[196:199], v[44:47]
	v_mfma_f32_16x16x32_bf16 v[36:39], v[162:165], v[196:199], v[36:39]
	v_mfma_f32_16x16x32_bf16 v[28:31], v[152:155], v[222:225], v[28:31]
	v_mfma_f32_16x16x32_bf16 v[20:23], v[162:165], v[222:225], v[20:23]
	v_mfma_f32_16x16x32_bf16 v[12:15], v[152:155], v[230:233], v[12:15]
	v_mfma_f32_16x16x32_bf16 v[4:7], v[162:165], v[230:233], v[4:7]
	v_mfma_f32_16x16x32_bf16 v[60:63], v[156:159], v[192:195], v[60:63]
	v_mfma_f32_16x16x32_bf16 v[52:55], v[166:169], v[192:195], v[52:55]
	v_mfma_f32_16x16x32_bf16 v[44:47], v[156:159], v[218:221], v[44:47]
	v_mfma_f32_16x16x32_bf16 v[36:39], v[166:169], v[218:221], v[36:39]
	v_mfma_f32_16x16x32_bf16 v[28:31], v[156:159], v[226:229], v[28:31]
	v_mfma_f32_16x16x32_bf16 v[20:23], v[166:169], v[226:229], v[20:23]
	v_mfma_f32_16x16x32_bf16 v[12:15], v[156:159], v[234:237], v[12:15]
	v_mfma_f32_16x16x32_bf16 v[4:7], v[166:169], v[234:237], v[4:7]
	s_setprio 0
	s_setprio 1
	v_mfma_f32_16x16x32_bf16 v[56:59], v[172:175], v[188:191], v[56:59]
	v_mfma_f32_16x16x32_bf16 v[48:51], v[180:183], v[188:191], v[48:51]
	v_mfma_f32_16x16x32_bf16 v[40:43], v[172:175], v[196:199], v[40:43]
	v_mfma_f32_16x16x32_bf16 v[32:35], v[180:183], v[196:199], v[32:35]
	v_mfma_f32_16x16x32_bf16 v[24:27], v[172:175], v[222:225], v[24:27]
	v_mfma_f32_16x16x32_bf16 v[16:19], v[180:183], v[222:225], v[16:19]
	v_mfma_f32_16x16x32_bf16 v[8:11], v[172:175], v[230:233], v[8:11]
	v_mfma_f32_16x16x32_bf16 v[0:3], v[180:183], v[230:233], v[0:3]
	v_mfma_f32_16x16x32_bf16 v[56:59], v[176:179], v[192:195], v[56:59]
	v_mfma_f32_16x16x32_bf16 v[48:51], v[184:187], v[192:195], v[48:51]
	v_mfma_f32_16x16x32_bf16 v[40:43], v[176:179], v[218:221], v[40:43]
	v_mfma_f32_16x16x32_bf16 v[32:35], v[184:187], v[218:221], v[32:35]
	v_mfma_f32_16x16x32_bf16 v[24:27], v[176:179], v[226:229], v[24:27]
	v_mfma_f32_16x16x32_bf16 v[16:19], v[184:187], v[226:229], v[16:19]
	v_mfma_f32_16x16x32_bf16 v[8:11], v[176:179], v[234:237], v[8:11]
	v_mfma_f32_16x16x32_bf16 v[0:3], v[184:187], v[234:237], v[0:3]
	s_setprio 0
	s_barrier
	s_add_i32 vcc_hi, vcc_hi, 2
	s_add_u32 s98, s98, 0x100
	s_addc_u32 s99, s99, 0
	s_add_u32 s46, s46, 0x100
	s_addc_u32 s47, s47, 0
	s_cmp_gt_u32 vcc_hi, 13
	s_cbranch_scc0 .LBB0_121
	s_branch .Lpeel_after_LBB0121

; #define PG8_STAGE(bufoff, gbase, voff) do { _Pragma("unroll") for (int _i = 0; _i < 2; ++_i) \
;         __builtin_amdgcn_global_load_lds((const unsigned*)((const char*)(gbase) + (voff)[_i]), (PG8_LAS unsigned*)(lds + (bufoff) + ldsw + _i * 8192), 16, 0, 0); } while (0)
; #define PG8_LDA(dst, b, h) do { _Pragma("unroll") for (int m = 0; m < 4; ++m) _Pragma("unroll") for (int k = 0; k < 2; ++k) dst[m][k] = *(const PG8_LAS bf16x8*)(lds + PG8_SA(b, h) + aoff + m * 2048 + k * 1024); } while (0)
; #define PG8_LDB(dst, b, h) do { _Pragma("unroll") for (int n = 0; n < 2; ++n) _Pragma("unroll") for (int k = 0; k < 2; ++k) dst[n][k] = *(const PG8_LAS bf16x8*)(lds + PG8_SB(b, h) + boff + n * 2048 + k * 1024); } while (0)
; #define PG8_WAIT_V(n) asm volatile("s_waitcnt vmcnt(" #n ")" ::: "memory")
; #define PG8_WAIT_L(n) asm volatile("s_waitcnt lgkmcnt(" #n ")" ::: "memory")
; #define PG8_BAR __builtin_amdgcn_s_barrier()
; #define PG8_SCHED __builtin_amdgcn_sched_barrier(0)
; template <class Epi, class Sched, bool ALIGN_EPI = false, bool SP2 = false>
; __device__ __forceinline__ void gemm_phase(PG8_LAS unsigned char* lds, const Gemm g, const Sched& S, const Epi& E) {
;     ...
;         const bool has_next = S.next(ui + 1, nxt);
;         const char* nA = has_next ? (const char*)g.A + (size_t)nxt.pm * tstep : cA; const char* nB = has_next ? (const char*)g.Bt + (size_t)nxt.pn * tstep : cB;
;         for (int t = 0; t < nt; t += 2) {
;             const bool last = (t == nt - 2);
;             const char* a1 = cA + (size_t)(t + 1) * kstep;
;             const char* a2 = last ? nA : cA + (size_t)(t + 2) * kstep; const char* b2 = last ? nB : cB + (size_t)(t + 2) * kstep;
;             const char* a3 = a2 + kstep; const char* b3 = b2 + kstep;
;             if (last && has_next) S.a_ready(nxt);
;             if constexpr (SP2) {
;             PG8_LDB(B0, 0, 0); PG8_LDB(B1, 0, 1); PG8_SCHED; PG8_LDA(At, 0, 0); PG8_STAGE(PG8_SA(1, 1), a1 + hstep, voffA);
;             PG8_WAIT_V(8); PG8_WAIT_L(0); PG8_BAR; PG8_MMA(0, 0, At, B0); PG8_MMA(0, 1, At, B1); PG8_BAR; PG8_SCHED;
;     ...
;         for (int a = 0; a < 2; ++a)
; #pragma unroll
;             for (int b = 0; b < 2; ++b)
; #pragma unroll
;                 for (int m = 0; m < 4; ++m)
; #pragma unroll
;                     for (int n = 0; n < 2; ++n) acc[a][b][m][n] = (f32x4){0.f, 0.f, 0.f, 0.f};
;         cur = nxt; cA = nA; cB = nB; ++ui;
.LBB0_177:
	s_add_u32 s66, s50, 0x80
	s_addc_u32 s67, s51, 0
	s_add_u32 s46, s26, 0x100
	v_mov_b32_e32 v0, 0
	s_addc_u32 s47, s27, 0
	s_mov_b32 s26, 0
	v_mov_b32_e32 v1, v0
	v_mov_b32_e32 v2, v0
	v_mov_b32_e32 v3, v0
	v_mov_b32_e32 v4, v0
	v_mov_b32_e32 v5, v0
	v_mov_b32_e32 v6, v0
	v_mov_b32_e32 v7, v0
	v_mov_b32_e32 v12, v0
	v_mov_b32_e32 v13, v0
	v_mov_b32_e32 v14, v0
	v_mov_b32_e32 v15, v0
	v_mov_b32_e32 v20, v0
	v_mov_b32_e32 v21, v0
	v_mov_b32_e32 v22, v0
	v_mov_b32_e32 v23, v0
	v_mov_b32_e32 v28, v0
	v_mov_b32_e32 v29, v0
	v_mov_b32_e32 v30, v0
	v_mov_b32_e32 v31, v0
	v_mov_b32_e32 v36, v0
	v_mov_b32_e32 v37, v0
	v_mov_b32_e32 v38, v0
	v_mov_b32_e32 v39, v0
	v_mov_b32_e32 v44, v0
	v_mov_b32_e32 v45, v0
	v_mov_b32_e32 v46, v0
	v_mov_b32_e32 v47, v0
	v_mov_b32_e32 v52, v0
	v_mov_b32_e32 v53, v0
	v_mov_b32_e32 v54, v0
	v_mov_b32_e32 v55, v0
	v_mov_b32_e32 v8, v0
	v_mov_b32_e32 v9, v0
	v_mov_b32_e32 v10, v0
	v_mov_b32_e32 v11, v0
	v_mov_b32_e32 v16, v0
	v_mov_b32_e32 v17, v0
	v_mov_b32_e32 v18, v0
	v_mov_b32_e32 v19, v0
	v_mov_b32_e32 v24, v0
	v_mov_b32_e32 v25, v0
	v_mov_b32_e32 v26, v0
	v_mov_b32_e32 v27, v0
	v_mov_b32_e32 v32, v0
	v_mov_b32_e32 v33, v0
	v_mov_b32_e32 v34, v0
	v_mov_b32_e32 v35, v0
	v_mov_b32_e32 v40, v0
	v_mov_b32_e32 v41, v0
	v_mov_b32_e32 v42, v0
	v_mov_b32_e32 v43, v0
	v_mov_b32_e32 v48, v0
	v_mov_b32_e32 v49, v0
	v_mov_b32_e32 v50, v0
	v_mov_b32_e32 v51, v0
	v_mov_b32_e32 v56, v0
	v_mov_b32_e32 v57, v0
	v_mov_b32_e32 v58, v0
	v_mov_b32_e32 v59, v0
	v_mov_b32_e32 v60, v0
	v_mov_b32_e32 v61, v0
	v_mov_b32_e32 v62, v0
	v_mov_b32_e32 v63, v0
	v_mov_b32_e32 v64, v0
	v_mov_b32_e32 v65, v0
	v_mov_b32_e32 v66, v0
	v_mov_b32_e32 v67, v0
	v_mov_b32_e32 v68, v0
	v_mov_b32_e32 v69, v0
	v_mov_b32_e32 v70, v0
	v_mov_b32_e32 v71, v0
	v_mov_b32_e32 v76, v0
	v_mov_b32_e32 v77, v0
	v_mov_b32_e32 v78, v0
	v_mov_b32_e32 v79, v0
	v_mov_b32_e32 v84, v0
	v_mov_b32_e32 v85, v0
	v_mov_b32_e32 v86, v0
	v_mov_b32_e32 v87, v0
	v_mov_b32_e32 v92, v0
	v_mov_b32_e32 v93, v0
	v_mov_b32_e32 v94, v0
	v_mov_b32_e32 v95, v0
	v_mov_b32_e32 v100, v0
	v_mov_b32_e32 v101, v0
	v_mov_b32_e32 v102, v0
	v_mov_b32_e32 v103, v0
	v_mov_b32_e32 v108, v0
	v_mov_b32_e32 v109, v0
	v_mov_b32_e32 v110, v0
	v_mov_b32_e32 v111, v0
	v_mov_b32_e32 v116, v0
	v_mov_b32_e32 v117, v0
	v_mov_b32_e32 v118, v0
	v_mov_b32_e32 v119, v0
	v_mov_b32_e32 v72, v0
	v_mov_b32_e32 v73, v0
	v_mov_b32_e32 v74, v0
	v_mov_b32_e32 v75, v0
	v_mov_b32_e32 v80, v0
	v_mov_b32_e32 v81, v0
	v_mov_b32_e32 v82, v0
	v_mov_b32_e32 v83, v0
	v_mov_b32_e32 v88, v0
	v_mov_b32_e32 v89, v0
	v_mov_b32_e32 v90, v0
	v_mov_b32_e32 v91, v0
	v_mov_b32_e32 v96, v0
	v_mov_b32_e32 v97, v0
	v_mov_b32_e32 v98, v0
	v_mov_b32_e32 v99, v0
	v_mov_b32_e32 v104, v0
	v_mov_b32_e32 v105, v0
	v_mov_b32_e32 v106, v0
	v_mov_b32_e32 v107, v0
	v_mov_b32_e32 v112, v0
	v_mov_b32_e32 v113, v0
	v_mov_b32_e32 v114, v0
	v_mov_b32_e32 v115, v0
	v_mov_b32_e32 v120, v0
	v_mov_b32_e32 v121, v0
	v_mov_b32_e32 v122, v0
	v_mov_b32_e32 v123, v0
	v_mov_b32_e32 v124, v0
	v_mov_b32_e32 v125, v0
	v_mov_b32_e32 v126, v0
	v_mov_b32_e32 v127, v0
	s_cmp_eq_u32 s85, 1
	s_cbranch_scc1 .LBB0_178
	s_add_i32 s50, s26, 2
	s_add_u32 s51, s66, 0x80
	s_addc_u32 s27, s67, 0
	s_add_i32 s52, 0, 0x10000
	s_cmp_eq_u32 s84, s26
	s_cselect_b32 s27, s11, s27
	s_cselect_b32 s26, s10, s51
	v_add_u32_e32 v138, s52, v141
	s_cselect_b32 s99, s65, s47
	s_cselect_b32 s98, s64, s46
	s_add_i32 s51, 0, 0x14000
	ds_read_b128 v[144:147], v138
	ds_read_b128 v[150:153], v138 offset:1024
	ds_read_b128 v[154:157], v138 offset:2048
	ds_read_b128 v[162:165], v138 offset:3072
	v_add_u32_e32 v138, s51, v141
	ds_read_b128 v[166:169], v138
	ds_read_b128 v[172:175], v138 offset:1024
	ds_read_b128 v[176:179], v138 offset:2048
	ds_read_b128 v[180:183], v138 offset:3072
	v_lshl_add_u64 v[138:139], s[66:67], 0, v[134:135]
	s_add_i32 m0, s37, 0xc000
	ds_read_b128 v[184:187], v143
	ds_read_b128 v[188:191], v143 offset:1024
	ds_read_b128 v[192:195], v143 offset:2048
	ds_read_b128 v[196:199], v143 offset:3072
	ds_read_b128 v[218:221], v143 offset:4096
	ds_read_b128 v[222:225], v143 offset:5120
	ds_read_b128 v[226:229], v143 offset:6144
	ds_read_b128 v[230:233], v143 offset:7168
	global_load_lds_dwordx4 v[138:139], off
	v_lshl_add_u64 v[138:139], s[66:67], 0, v[136:137]
	s_add_i32 m0, s37, 0xe000
	s_nop 0
	global_load_lds_dwordx4 v[138:139], off
	s_waitcnt vmcnt(24)
	s_waitcnt lgkmcnt(0)
	s_barrier
	s_setprio 1
	s_waitcnt lgkmcnt(0)
	v_mfma_f32_16x16x32_bf16 v[124:127], v[144:147], v[184:187], v[124:127]
	v_mfma_f32_16x16x32_bf16 v[120:123], v[154:157], v[184:187], v[120:123]
	v_mfma_f32_16x16x32_bf16 v[112:115], v[144:147], v[192:195], v[112:115]
	v_mfma_f32_16x16x32_bf16 v[104:107], v[154:157], v[192:195], v[104:107]
	v_mfma_f32_16x16x32_bf16 v[96:99], v[144:147], v[218:221], v[96:99]
	v_mfma_f32_16x16x32_bf16 v[88:91], v[154:157], v[218:221], v[88:91]
	v_mfma_f32_16x16x32_bf16 v[80:83], v[144:147], v[226:229], v[80:83]
	v_mfma_f32_16x16x32_bf16 v[72:75], v[154:157], v[226:229], v[72:75]
	v_mfma_f32_16x16x32_bf16 v[124:127], v[150:153], v[188:191], v[124:127]
	v_mfma_f32_16x16x32_bf16 v[120:123], v[162:165], v[188:191], v[120:123]
	v_mfma_f32_16x16x32_bf16 v[112:115], v[150:153], v[196:199], v[112:115]
	v_mfma_f32_16x16x32_bf16 v[104:107], v[162:165], v[196:199], v[104:107]
	v_mfma_f32_16x16x32_bf16 v[96:99], v[150:153], v[222:225], v[96:99]
	v_mfma_f32_16x16x32_bf16 v[88:91], v[162:165], v[222:225], v[88:91]
	v_mfma_f32_16x16x32_bf16 v[80:83], v[150:153], v[230:233], v[80:83]
	v_mfma_f32_16x16x32_bf16 v[72:75], v[162:165], v[230:233], v[72:75]
	s_setprio 0
	s_setprio 1
	v_mfma_f32_16x16x32_bf16 v[116:119], v[166:169], v[184:187], v[116:119]
	v_mfma_f32_16x16x32_bf16 v[108:111], v[176:179], v[184:187], v[108:111]
	v_mfma_f32_16x16x32_bf16 v[100:103], v[166:169], v[192:195], v[100:103]
	v_mfma_f32_16x16x32_bf16 v[92:95], v[176:179], v[192:195], v[92:95]
	v_mfma_f32_16x16x32_bf16 v[84:87], v[166:169], v[218:221], v[84:87]
	v_mfma_f32_16x16x32_bf16 v[76:79], v[176:179], v[218:221], v[76:79]
	v_mfma_f32_16x16x32_bf16 v[68:71], v[166:169], v[226:229], v[68:71]
	v_mfma_f32_16x16x32_bf16 v[64:67], v[176:179], v[226:229], v[64:67]
	v_mfma_f32_16x16x32_bf16 v[116:119], v[172:175], v[188:191], v[116:119]
	v_mfma_f32_16x16x32_bf16 v[108:111], v[180:183], v[188:191], v[108:111]
	v_mfma_f32_16x16x32_bf16 v[100:103], v[172:175], v[196:199], v[100:103]
	v_mfma_f32_16x16x32_bf16 v[92:95], v[180:183], v[196:199], v[92:95]
	v_mfma_f32_16x16x32_bf16 v[84:87], v[172:175], v[222:225], v[84:87]
	v_mfma_f32_16x16x32_bf16 v[76:79], v[180:183], v[222:225], v[76:79]
	v_mfma_f32_16x16x32_bf16 v[68:71], v[172:175], v[230:233], v[68:71]
	v_mfma_f32_16x16x32_bf16 v[64:67], v[180:183], v[230:233], v[64:67]
	s_setprio 0
	s_barrier
; #define PG8_STAGE(bufoff, gbase, voff) do { _Pragma("unroll") for (int _i = 0; _i < 2; ++_i) \
;         __builtin_amdgcn_global_load_lds((const unsigned*)((const char*)(gbase) + (voff)[_i]), (PG8_LAS unsigned*)(lds + (bufoff) + ldsw + _i * 8192), 16, 0, 0); } while (0)
; #define PG8_LDA(dst, b, h) do { _Pragma("unroll") for (int m = 0; m < 4; ++m) _Pragma("unroll") for (int k = 0; k < 2; ++k) dst[m][k] = *(const PG8_LAS bf16x8*)(lds + PG8_SA(b, h) + aoff + m * 2048 + k * 1024); } while (0)
; #define PG8_LDB(dst, b, h) do { _Pragma("unroll") for (int n = 0; n < 2; ++n) _Pragma("unroll") for (int k = 0; k < 2; ++k) dst[n][k] = *(const PG8_LAS bf16x8*)(lds + PG8_SB(b, h) + boff + n * 2048 + k * 1024); } while (0)
; #define PG8_MMA(ai, bj, At, Bt) do { __builtin_amdgcn_s_setprio(1); _Pragma("unroll") for (int m = 0; m < 4; ++m) _Pragma("unroll") for (int n = 0; n < 2; ++n) _Pragma("unroll") for (int k = 0; k < 2; ++k) \
;         acc[ai][bj][m][n] = __builtin_amdgcn_mfma_f32_16x16x32_bf16(Bt[n][k], At[m][k], acc[ai][bj][m][n], 0, 0, 0); __builtin_amdgcn_s_setprio(0); } while (0)
; #define PG8_WAIT_V(n) asm volatile("s_waitcnt vmcnt(" #n ")" ::: "memory")
; #define PG8_WAIT_L(n) asm volatile("s_waitcnt lgkmcnt(" #n ")" ::: "memory")
; #define PG8_BAR __builtin_amdgcn_s_barrier()
; #define PG8_SCHED __builtin_amdgcn_sched_barrier(0)
; template <class Epi, class Sched, bool ALIGN_EPI = false, bool SP2 = false>
; __device__ __forceinline__ void gemm_phase(PG8_LAS unsigned char* lds, const Gemm g, const Sched& S, const Epi& E) {
;     ...
;             PG8_LDA(At, 0, 1); PG8_STAGE(PG8_SB(0, 0), b2, voffB); PG8_STAGE(PG8_SB(0, 1), b2 + hstep, voffB); PG8_STAGE(PG8_SA(0, 0), a2, voffA);
;             PG8_WAIT_V(8); PG8_WAIT_L(0); PG8_BAR; PG8_MMA(1, 0, At, B0); PG8_MMA(1, 1, At, B1); PG8_BAR; PG8_SCHED;
;             PG8_LDB(B0, 1, 0); PG8_LDB(B1, 1, 1); PG8_SCHED; PG8_LDA(At, 1, 0); PG8_STAGE(PG8_SA(0, 1), a2 + hstep, voffA);
;             PG8_WAIT_V(8); PG8_WAIT_L(0); PG8_BAR; PG8_MMA(0, 0, At, B0); PG8_MMA(0, 1, At, B1); PG8_BAR; PG8_SCHED;
	s_add_i32 s52, s52, s19
	v_lshl_add_u64 v[138:139], s[98:99], 0, v[160:161]
	s_mov_b32 m0, s52
	ds_read_b128 v[184:187], v143 offset:16384
	ds_read_b128 v[188:191], v143 offset:17408
	ds_read_b128 v[192:195], v143 offset:18432
	ds_read_b128 v[196:199], v143 offset:19456
	ds_read_b128 v[218:221], v143 offset:20480
	ds_read_b128 v[222:225], v143 offset:21504
	ds_read_b128 v[226:229], v143 offset:22528
	ds_read_b128 v[230:233], v143 offset:23552
	global_load_lds_dwordx4 v[138:139], off
	s_add_i32 m0, s52, 0x2000
	v_lshl_add_u64 v[158:159], s[98:99], 0, v[128:129]
	s_add_u32 s98, s98, s72
	s_addc_u32 s99, s99, 0
	s_add_i32 s51, s51, s19
	global_load_lds_dwordx4 v[158:159], off
	v_lshl_add_u64 v[234:235], s[98:99], 0, v[160:161]
	s_mov_b32 m0, s51
	v_lshl_add_u64 v[236:237], s[98:99], 0, v[128:129]
	global_load_lds_dwordx4 v[234:235], off
	s_add_i32 m0, s51, 0x2000
	v_lshl_add_u64 v[238:239], s[26:27], 0, v[132:133]
	global_load_lds_dwordx4 v[236:237], off
	s_mov_b32 m0, s37
	v_lshl_add_u64 v[240:241], s[26:27], 0, v[130:131]
	global_load_lds_dwordx4 v[238:239], off
	s_mov_b32 m0, s68
	s_nop 0
	global_load_lds_dwordx4 v[240:241], off
	s_waitcnt vmcnt(24)
	s_waitcnt lgkmcnt(0)
	s_barrier
	s_setprio 1
	s_waitcnt lgkmcnt(0)
	v_mfma_f32_16x16x32_bf16 v[60:63], v[144:147], v[184:187], v[60:63]
	v_mfma_f32_16x16x32_bf16 v[56:59], v[154:157], v[184:187], v[56:59]
	v_mfma_f32_16x16x32_bf16 v[48:51], v[144:147], v[192:195], v[48:51]
	v_mfma_f32_16x16x32_bf16 v[40:43], v[154:157], v[192:195], v[40:43]
	v_mfma_f32_16x16x32_bf16 v[32:35], v[144:147], v[218:221], v[32:35]
	v_mfma_f32_16x16x32_bf16 v[24:27], v[154:157], v[218:221], v[24:27]
	v_mfma_f32_16x16x32_bf16 v[16:19], v[144:147], v[226:229], v[16:19]
	v_mfma_f32_16x16x32_bf16 v[8:11], v[154:157], v[226:229], v[8:11]
	v_mfma_f32_16x16x32_bf16 v[60:63], v[150:153], v[188:191], v[60:63]
	v_mfma_f32_16x16x32_bf16 v[56:59], v[162:165], v[188:191], v[56:59]
	v_mfma_f32_16x16x32_bf16 v[48:51], v[150:153], v[196:199], v[48:51]
	v_mfma_f32_16x16x32_bf16 v[40:43], v[162:165], v[196:199], v[40:43]
	v_mfma_f32_16x16x32_bf16 v[32:35], v[150:153], v[222:225], v[32:35]
	v_mfma_f32_16x16x32_bf16 v[24:27], v[162:165], v[222:225], v[24:27]
	v_mfma_f32_16x16x32_bf16 v[16:19], v[150:153], v[230:233], v[16:19]
	v_mfma_f32_16x16x32_bf16 v[8:11], v[162:165], v[230:233], v[8:11]
	s_setprio 0
	s_setprio 1
	v_mfma_f32_16x16x32_bf16 v[52:55], v[166:169], v[184:187], v[52:55]
	v_mfma_f32_16x16x32_bf16 v[44:47], v[176:179], v[184:187], v[44:47]
	v_mfma_f32_16x16x32_bf16 v[36:39], v[166:169], v[192:195], v[36:39]
	v_mfma_f32_16x16x32_bf16 v[28:31], v[176:179], v[192:195], v[28:31]
	v_mfma_f32_16x16x32_bf16 v[20:23], v[166:169], v[218:221], v[20:23]
	v_mfma_f32_16x16x32_bf16 v[12:15], v[176:179], v[218:221], v[12:15]
	v_mfma_f32_16x16x32_bf16 v[4:7], v[166:169], v[226:229], v[4:7]
	v_mfma_f32_16x16x32_bf16 v[0:3], v[176:179], v[226:229], v[0:3]
	v_mfma_f32_16x16x32_bf16 v[52:55], v[172:175], v[188:191], v[52:55]
	v_mfma_f32_16x16x32_bf16 v[44:47], v[180:183], v[188:191], v[44:47]
	v_mfma_f32_16x16x32_bf16 v[36:39], v[172:175], v[196:199], v[36:39]
	v_mfma_f32_16x16x32_bf16 v[28:31], v[180:183], v[196:199], v[28:31]
	v_mfma_f32_16x16x32_bf16 v[20:23], v[172:175], v[222:225], v[20:23]
	v_mfma_f32_16x16x32_bf16 v[12:15], v[180:183], v[222:225], v[12:15]
	v_mfma_f32_16x16x32_bf16 v[4:7], v[172:175], v[230:233], v[4:7]
	v_mfma_f32_16x16x32_bf16 v[0:3], v[180:183], v[230:233], v[0:3]
	s_setprio 0
	s_barrier
	s_add_i32 s51, 0, 0x18000
	v_add_u32_e32 v149, s51, v141
	s_add_i32 s52, 0, 0x1c000
	ds_read_b128 v[144:147], v149
	ds_read_b128 v[150:153], v149 offset:1024
	ds_read_b128 v[154:157], v149 offset:2048
	ds_read_b128 v[162:165], v149 offset:3072
	v_add_u32_e32 v149, s52, v141
	ds_read_b128 v[166:169], v149
	ds_read_b128 v[172:175], v149 offset:1024
	ds_read_b128 v[176:179], v149 offset:2048
	ds_read_b128 v[180:183], v149 offset:3072
	s_add_u32 s26, s26, s72
	s_addc_u32 s27, s27, 0
	s_mov_b32 m0, s69
	v_lshl_add_u64 v[242:243], s[26:27], 0, v[132:133]
	ds_read_b128 v[184:187], v143 offset:32768
	ds_read_b128 v[188:191], v143 offset:33792
	ds_read_b128 v[192:195], v143 offset:34816
	ds_read_b128 v[196:199], v143 offset:35840
	ds_read_b128 v[218:221], v143 offset:36864
	ds_read_b128 v[222:225], v143 offset:37888
	ds_read_b128 v[226:229], v143 offset:38912
	ds_read_b128 v[230:233], v143 offset:39936
	global_load_lds_dwordx4 v[242:243], off
	v_lshl_add_u64 v[242:243], s[26:27], 0, v[130:131]
	s_mov_b32 m0, s70
	s_nop 0
	global_load_lds_dwordx4 v[242:243], off
	s_waitcnt vmcnt(8)
	s_waitcnt lgkmcnt(0)
	s_barrier
; #define PG8_STAGE(bufoff, gbase, voff) do { _Pragma("unroll") for (int _i = 0; _i < 2; ++_i) \
;         __builtin_amdgcn_global_load_lds((const unsigned*)((const char*)(gbase) + (voff)[_i]), (PG8_LAS unsigned*)(lds + (bufoff) + ldsw + _i * 8192), 16, 0, 0); } while (0)
; #define PG8_LDA(dst, b, h) do { _Pragma("unroll") for (int m = 0; m < 4; ++m) _Pragma("unroll") for (int k = 0; k < 2; ++k) dst[m][k] = *(const PG8_LAS bf16x8*)(lds + PG8_SA(b, h) + aoff + m * 2048 + k * 1024); } while (0)
; #define PG8_MMA(ai, bj, At, Bt) do { __builtin_amdgcn_s_setprio(1); _Pragma("unroll") for (int m = 0; m < 4; ++m) _Pragma("unroll") for (int n = 0; n < 2; ++n) _Pragma("unroll") for (int k = 0; k < 2; ++k) \
;         acc[ai][bj][m][n] = __builtin_amdgcn_mfma_f32_16x16x32_bf16(Bt[n][k], At[m][k], acc[ai][bj][m][n], 0, 0, 0); __builtin_amdgcn_s_setprio(0); } while (0)
; #define PG8_WAIT_V(n) asm volatile("s_waitcnt vmcnt(" #n ")" ::: "memory")
; #define PG8_WAIT_L(n) asm volatile("s_waitcnt lgkmcnt(" #n ")" ::: "memory")
; #define PG8_BAR __builtin_amdgcn_s_barrier()
; #define PG8_SCHED __builtin_amdgcn_sched_barrier(0)
; template <class Epi, class Sched, bool ALIGN_EPI = false, bool SP2 = false>
; __device__ __forceinline__ void gemm_phase(PG8_LAS unsigned char* lds, const Gemm g, const Sched& S, const Epi& E) {
;     ...
;         for (int t = 0; t < nt; t += 2) {
;             const bool last = (t == nt - 2);
;             const char* a1 = cA + (size_t)(t + 1) * kstep;
;             const char* a2 = last ? nA : cA + (size_t)(t + 2) * kstep; const char* b2 = last ? nB : cB + (size_t)(t + 2) * kstep;
;     ...
;             PG8_WAIT_V(8); PG8_WAIT_L(0); PG8_BAR; PG8_MMA(0, 0, At, B0); PG8_MMA(0, 1, At, B1); PG8_BAR; PG8_SCHED;
;             PG8_LDA(At, 1, 1); PG8_STAGE(PG8_SB(1, 0), b3, voffB); PG8_STAGE(PG8_SB(1, 1), b3 + hstep, voffB); PG8_STAGE(PG8_SA(1, 0), a3, voffA);
;             PG8_WAIT_V(8); PG8_WAIT_L(0); PG8_BAR; PG8_MMA(1, 0, At, B0); PG8_MMA(1, 1, At, B1); PG8_BAR; PG8_SCHED;
	s_setprio 1
	s_waitcnt lgkmcnt(0)
	v_mfma_f32_16x16x32_bf16 v[124:127], v[144:147], v[184:187], v[124:127]
	v_mfma_f32_16x16x32_bf16 v[120:123], v[154:157], v[184:187], v[120:123]
	v_mfma_f32_16x16x32_bf16 v[112:115], v[144:147], v[192:195], v[112:115]
	v_mfma_f32_16x16x32_bf16 v[104:107], v[154:157], v[192:195], v[104:107]
	v_mfma_f32_16x16x32_bf16 v[96:99], v[144:147], v[218:221], v[96:99]
	v_mfma_f32_16x16x32_bf16 v[88:91], v[154:157], v[218:221], v[88:91]
	v_mfma_f32_16x16x32_bf16 v[80:83], v[144:147], v[226:229], v[80:83]
	v_mfma_f32_16x16x32_bf16 v[72:75], v[154:157], v[226:229], v[72:75]
	v_mfma_f32_16x16x32_bf16 v[124:127], v[150:153], v[188:191], v[124:127]
	v_mfma_f32_16x16x32_bf16 v[120:123], v[162:165], v[188:191], v[120:123]
	v_mfma_f32_16x16x32_bf16 v[112:115], v[150:153], v[196:199], v[112:115]
	v_mfma_f32_16x16x32_bf16 v[104:107], v[162:165], v[196:199], v[104:107]
	v_mfma_f32_16x16x32_bf16 v[96:99], v[150:153], v[222:225], v[96:99]
	v_mfma_f32_16x16x32_bf16 v[88:91], v[162:165], v[222:225], v[88:91]
	v_mfma_f32_16x16x32_bf16 v[80:83], v[150:153], v[230:233], v[80:83]
	v_mfma_f32_16x16x32_bf16 v[72:75], v[162:165], v[230:233], v[72:75]
	s_setprio 0
	s_setprio 1
	v_mfma_f32_16x16x32_bf16 v[116:119], v[166:169], v[184:187], v[116:119]
	v_mfma_f32_16x16x32_bf16 v[108:111], v[176:179], v[184:187], v[108:111]
	v_mfma_f32_16x16x32_bf16 v[100:103], v[166:169], v[192:195], v[100:103]
	v_mfma_f32_16x16x32_bf16 v[92:95], v[176:179], v[192:195], v[92:95]
	v_mfma_f32_16x16x32_bf16 v[84:87], v[166:169], v[218:221], v[84:87]
	v_mfma_f32_16x16x32_bf16 v[76:79], v[176:179], v[218:221], v[76:79]
	v_mfma_f32_16x16x32_bf16 v[68:71], v[166:169], v[226:229], v[68:71]
	v_mfma_f32_16x16x32_bf16 v[64:67], v[176:179], v[226:229], v[64:67]
	v_mfma_f32_16x16x32_bf16 v[116:119], v[172:175], v[188:191], v[116:119]
	v_mfma_f32_16x16x32_bf16 v[108:111], v[180:183], v[188:191], v[108:111]
	v_mfma_f32_16x16x32_bf16 v[100:103], v[172:175], v[196:199], v[100:103]
	v_mfma_f32_16x16x32_bf16 v[92:95], v[180:183], v[196:199], v[92:95]
	v_mfma_f32_16x16x32_bf16 v[84:87], v[172:175], v[222:225], v[84:87]
	v_mfma_f32_16x16x32_bf16 v[76:79], v[180:183], v[222:225], v[76:79]
	v_mfma_f32_16x16x32_bf16 v[68:71], v[172:175], v[230:233], v[68:71]
	v_mfma_f32_16x16x32_bf16 v[64:67], v[180:183], v[230:233], v[64:67]
	s_setprio 0
	s_barrier
	s_add_i32 s26, s51, s19
	v_lshl_add_u64 v[138:139], v[138:139], 0, s[90:91]
	s_mov_b32 m0, s26
	ds_read_b128 v[184:187], v143 offset:49152
	ds_read_b128 v[188:191], v143 offset:50176
	ds_read_b128 v[192:195], v143 offset:51200
	ds_read_b128 v[196:199], v143 offset:52224
	ds_read_b128 v[218:221], v143 offset:53248
	ds_read_b128 v[222:225], v143 offset:54272
	ds_read_b128 v[226:229], v143 offset:55296
	ds_read_b128 v[230:233], v143 offset:56320
	global_load_lds_dwordx4 v[138:139], off
	v_lshl_add_u64 v[138:139], v[158:159], 0, s[90:91]
	s_add_i32 m0, s26, 0x2000
	s_add_i32 s26, s52, s19
	global_load_lds_dwordx4 v[138:139], off
	v_lshl_add_u64 v[138:139], v[234:235], 0, s[90:91]
	s_mov_b32 m0, s26
	s_nop 0
	global_load_lds_dwordx4 v[138:139], off
	v_lshl_add_u64 v[138:139], v[236:237], 0, s[90:91]
	s_add_i32 m0, s26, 0x2000
	s_nop 0
	global_load_lds_dwordx4 v[138:139], off
	v_lshl_add_u64 v[138:139], v[238:239], 0, s[90:91]
	s_mov_b32 m0, s80
	s_nop 0
	global_load_lds_dwordx4 v[138:139], off
	v_lshl_add_u64 v[138:139], v[240:241], 0, s[90:91]
	s_mov_b32 m0, s81
	s_nop 0
	global_load_lds_dwordx4 v[138:139], off
	s_waitcnt vmcnt(8)
	s_waitcnt lgkmcnt(0)
	s_barrier
	s_setprio 1
	s_waitcnt lgkmcnt(0)
	v_mfma_f32_16x16x32_bf16 v[60:63], v[144:147], v[184:187], v[60:63]
	v_mfma_f32_16x16x32_bf16 v[56:59], v[154:157], v[184:187], v[56:59]
	v_mfma_f32_16x16x32_bf16 v[48:51], v[144:147], v[192:195], v[48:51]
	v_mfma_f32_16x16x32_bf16 v[40:43], v[154:157], v[192:195], v[40:43]
	v_mfma_f32_16x16x32_bf16 v[32:35], v[144:147], v[218:221], v[32:35]
	v_mfma_f32_16x16x32_bf16 v[24:27], v[154:157], v[218:221], v[24:27]
	v_mfma_f32_16x16x32_bf16 v[16:19], v[144:147], v[226:229], v[16:19]
	v_mfma_f32_16x16x32_bf16 v[8:11], v[154:157], v[226:229], v[8:11]
	v_mfma_f32_16x16x32_bf16 v[60:63], v[150:153], v[188:191], v[60:63]
	v_mfma_f32_16x16x32_bf16 v[56:59], v[162:165], v[188:191], v[56:59]
	v_mfma_f32_16x16x32_bf16 v[48:51], v[150:153], v[196:199], v[48:51]
	v_mfma_f32_16x16x32_bf16 v[40:43], v[162:165], v[196:199], v[40:43]
	v_mfma_f32_16x16x32_bf16 v[32:35], v[150:153], v[222:225], v[32:35]
	v_mfma_f32_16x16x32_bf16 v[24:27], v[162:165], v[222:225], v[24:27]
	v_mfma_f32_16x16x32_bf16 v[16:19], v[150:153], v[230:233], v[16:19]
	v_mfma_f32_16x16x32_bf16 v[8:11], v[162:165], v[230:233], v[8:11]
	s_setprio 0
	s_setprio 1
	v_mfma_f32_16x16x32_bf16 v[52:55], v[166:169], v[184:187], v[52:55]
	v_mfma_f32_16x16x32_bf16 v[44:47], v[176:179], v[184:187], v[44:47]
	v_mfma_f32_16x16x32_bf16 v[36:39], v[166:169], v[192:195], v[36:39]
	v_mfma_f32_16x16x32_bf16 v[28:31], v[176:179], v[192:195], v[28:31]
	v_mfma_f32_16x16x32_bf16 v[20:23], v[166:169], v[218:221], v[20:23]
	v_mfma_f32_16x16x32_bf16 v[12:15], v[176:179], v[218:221], v[12:15]
	v_mfma_f32_16x16x32_bf16 v[4:7], v[166:169], v[226:229], v[4:7]
	v_mfma_f32_16x16x32_bf16 v[0:3], v[176:179], v[226:229], v[0:3]
	v_mfma_f32_16x16x32_bf16 v[52:55], v[172:175], v[188:191], v[52:55]
	v_mfma_f32_16x16x32_bf16 v[44:47], v[180:183], v[188:191], v[44:47]
	v_mfma_f32_16x16x32_bf16 v[36:39], v[172:175], v[196:199], v[36:39]
	v_mfma_f32_16x16x32_bf16 v[28:31], v[180:183], v[196:199], v[28:31]
	v_mfma_f32_16x16x32_bf16 v[20:23], v[172:175], v[222:225], v[20:23]
	v_mfma_f32_16x16x32_bf16 v[12:15], v[180:183], v[222:225], v[12:15]
	v_mfma_f32_16x16x32_bf16 v[4:7], v[172:175], v[230:233], v[4:7]
	v_mfma_f32_16x16x32_bf16 v[0:3], v[180:183], v[230:233], v[0:3]
	s_setprio 0
	s_barrier
	s_add_u32 s66, s66, 0x100
	s_addc_u32 s67, s67, 0
	s_add_u32 s46, s46, 0x100
	s_addc_u32 s47, s47, 0
	s_cmp_ge_u32 s50, s71
	s_mov_b32 s26, s50
	s_cbranch_scc0 .LBB0_178
	s_branch .Lpeel_after_LBB0178

; #define PG8_BAR __builtin_amdgcn_s_barrier()
; template <class Epi, class Sched, bool ALIGN_EPI = false, bool SP2 = false>
; __device__ __forceinline__ void gemm_phase(PG8_LAS unsigned char* lds, const Gemm g, const Sched& S, const Epi& E) {
;     ...
;         if constexpr (ALIGN_EPI) { if (wr == 0) PG8_BAR; }
.Lpeel_after_LBB0178:
	s_and_b64 vcc, exec, s[62:63]
	s_cbranch_vccz .LBB0_181
	s_barrier

; #define PG8_STAGE(bufoff, gbase, voff) do { _Pragma("unroll") for (int _i = 0; _i < 2; ++_i) \
;         __builtin_amdgcn_global_load_lds((const unsigned*)((const char*)(gbase) + (voff)[_i]), (PG8_LAS unsigned*)(lds + (bufoff) + ldsw + _i * 8192), 16, 0, 0); } while (0)
; #define PG8_LDA(dst, b, h) do { _Pragma("unroll") for (int m = 0; m < 4; ++m) _Pragma("unroll") for (int k = 0; k < 2; ++k) dst[m][k] = *(const PG8_LAS bf16x8*)(lds + PG8_SA(b, h) + aoff + m * 2048 + k * 1024); } while (0)
; #define PG8_LDB(dst, b, h) do { _Pragma("unroll") for (int n = 0; n < 2; ++n) _Pragma("unroll") for (int k = 0; k < 2; ++k) dst[n][k] = *(const PG8_LAS bf16x8*)(lds + PG8_SB(b, h) + boff + n * 2048 + k * 1024); } while (0)
; #define PG8_WAIT_V(n) asm volatile("s_waitcnt vmcnt(" #n ")" ::: "memory")
; #define PG8_WAIT_L(n) asm volatile("s_waitcnt lgkmcnt(" #n ")" ::: "memory")
; #define PG8_BAR __builtin_amdgcn_s_barrier()
; #define PG8_SCHED __builtin_amdgcn_sched_barrier(0)
; template <class Epi, class Sched, bool ALIGN_EPI = false, bool SP2 = false>
; __device__ __forceinline__ void gemm_phase(PG8_LAS unsigned char* lds, const Gemm g, const Sched& S, const Epi& E) {
;     ...
;         const bool has_next = S.next(ui + 1, nxt);
;         const char* nA = has_next ? (const char*)g.A + (size_t)nxt.pm * tstep : cA; const char* nB = has_next ? (const char*)g.Bt + (size_t)nxt.pn * tstep : cB;
;         for (int t = 0; t < nt; t += 2) {
;             const bool last = (t == nt - 2);
;             const char* a1 = cA + (size_t)(t + 1) * kstep;
;             const char* a2 = last ? nA : cA + (size_t)(t + 2) * kstep; const char* b2 = last ? nB : cB + (size_t)(t + 2) * kstep;
;             const char* a3 = a2 + kstep; const char* b3 = b2 + kstep;
;             if (last && has_next) S.a_ready(nxt);
;             if constexpr (SP2) {
;             PG8_LDB(B0, 0, 0); PG8_LDB(B1, 0, 1); PG8_SCHED; PG8_LDA(At, 0, 0); PG8_STAGE(PG8_SA(1, 1), a1 + hstep, voffA);
;             PG8_WAIT_V(8); PG8_WAIT_L(0); PG8_BAR; PG8_MMA(0, 0, At, B0); PG8_MMA(0, 1, At, B1); PG8_BAR; PG8_SCHED;
;     ...
;         for (int a = 0; a < 2; ++a)
; #pragma unroll
;             for (int b = 0; b < 2; ++b)
; #pragma unroll
;                 for (int m = 0; m < 4; ++m)
; #pragma unroll
;                     for (int n = 0; n < 2; ++n) acc[a][b][m][n] = (f32x4){0.f, 0.f, 0.f, 0.f};
;         cur = nxt; cA = nA; cB = nB; ++ui;
.LBB0_218:
	s_ashr_i32 s99, s98, 31
	s_lshl_b64 s[20:21], s[98:99], 19
	s_add_u32 s86, s60, s20
	s_addc_u32 s87, s61, s21
	s_and_b64 s[20:21], s[14:15], exec
	s_cselect_b32 s99, s87, s7
	s_cselect_b32 vcc_lo, s86, s6
	s_ashr_i32 s5, s4, 31
	s_lshl_b64 s[20:21], s[4:5], 19
	s_add_u32 s62, s37, s20
	s_addc_u32 s63, s50, s21
	s_and_b64 s[20:21], s[14:15], exec
	s_cselect_b32 s5, s63, s17
	s_cselect_b32 vcc_hi, s62, s16
	s_add_u32 s6, s6, 0x40080
	s_addc_u32 s7, s7, 0
	s_add_u32 s46, s16, 0x100
	v_mov_b32_e32 v0, 0
	s_addc_u32 s47, s17, 0
	s_mov_b32 s20, -2
	v_mov_b32_e32 v1, v0
	v_mov_b32_e32 v2, v0
	v_mov_b32_e32 v3, v0
	v_mov_b32_e32 v4, v0
	v_mov_b32_e32 v5, v0
	v_mov_b32_e32 v6, v0
	v_mov_b32_e32 v7, v0
	v_mov_b32_e32 v12, v0
	v_mov_b32_e32 v13, v0
	v_mov_b32_e32 v14, v0
	v_mov_b32_e32 v15, v0
	v_mov_b32_e32 v20, v0
	v_mov_b32_e32 v21, v0
	v_mov_b32_e32 v22, v0
	v_mov_b32_e32 v23, v0
	v_mov_b32_e32 v28, v0
	v_mov_b32_e32 v29, v0
	v_mov_b32_e32 v30, v0
	v_mov_b32_e32 v31, v0
	v_mov_b32_e32 v36, v0
	v_mov_b32_e32 v37, v0
	v_mov_b32_e32 v38, v0
	v_mov_b32_e32 v39, v0
	v_mov_b32_e32 v44, v0
	v_mov_b32_e32 v45, v0
	v_mov_b32_e32 v46, v0
	v_mov_b32_e32 v47, v0
	v_mov_b32_e32 v52, v0
	v_mov_b32_e32 v53, v0
	v_mov_b32_e32 v54, v0
	v_mov_b32_e32 v55, v0
	v_mov_b32_e32 v8, v0
	v_mov_b32_e32 v9, v0
	v_mov_b32_e32 v10, v0
	v_mov_b32_e32 v11, v0
	v_mov_b32_e32 v16, v0
	v_mov_b32_e32 v17, v0
	v_mov_b32_e32 v18, v0
	v_mov_b32_e32 v19, v0
	v_mov_b32_e32 v24, v0
	v_mov_b32_e32 v25, v0
	v_mov_b32_e32 v26, v0
	v_mov_b32_e32 v27, v0
	v_mov_b32_e32 v32, v0
	v_mov_b32_e32 v33, v0
	v_mov_b32_e32 v34, v0
	v_mov_b32_e32 v35, v0
	v_mov_b32_e32 v40, v0
	v_mov_b32_e32 v41, v0
	v_mov_b32_e32 v42, v0
	v_mov_b32_e32 v43, v0
	v_mov_b32_e32 v48, v0
	v_mov_b32_e32 v49, v0
	v_mov_b32_e32 v50, v0
	v_mov_b32_e32 v51, v0
	v_mov_b32_e32 v56, v0
	v_mov_b32_e32 v57, v0
	v_mov_b32_e32 v58, v0
	v_mov_b32_e32 v59, v0
	v_mov_b32_e32 v60, v0
	v_mov_b32_e32 v61, v0
	v_mov_b32_e32 v62, v0
	v_mov_b32_e32 v63, v0
	v_mov_b32_e32 v64, v0
	v_mov_b32_e32 v65, v0
	v_mov_b32_e32 v66, v0
	v_mov_b32_e32 v67, v0
	v_mov_b32_e32 v68, v0
	v_mov_b32_e32 v69, v0
	v_mov_b32_e32 v70, v0
	v_mov_b32_e32 v71, v0
	v_mov_b32_e32 v76, v0
	v_mov_b32_e32 v77, v0
	v_mov_b32_e32 v78, v0
	v_mov_b32_e32 v79, v0
	v_mov_b32_e32 v84, v0
	v_mov_b32_e32 v85, v0
	v_mov_b32_e32 v86, v0
	v_mov_b32_e32 v87, v0
	v_mov_b32_e32 v92, v0
	v_mov_b32_e32 v93, v0
	v_mov_b32_e32 v94, v0
	v_mov_b32_e32 v95, v0
	v_mov_b32_e32 v100, v0
	v_mov_b32_e32 v101, v0
	v_mov_b32_e32 v102, v0
	v_mov_b32_e32 v103, v0
	v_mov_b32_e32 v108, v0
	v_mov_b32_e32 v109, v0
	v_mov_b32_e32 v110, v0
	v_mov_b32_e32 v111, v0
	v_mov_b32_e32 v116, v0
	v_mov_b32_e32 v117, v0
	v_mov_b32_e32 v118, v0
	v_mov_b32_e32 v119, v0
	v_mov_b32_e32 v72, v0
	v_mov_b32_e32 v73, v0
	v_mov_b32_e32 v74, v0
	v_mov_b32_e32 v75, v0
	v_mov_b32_e32 v80, v0
	v_mov_b32_e32 v81, v0
	v_mov_b32_e32 v82, v0
	v_mov_b32_e32 v83, v0
	v_mov_b32_e32 v88, v0
	v_mov_b32_e32 v89, v0
	v_mov_b32_e32 v90, v0
	v_mov_b32_e32 v91, v0
	v_mov_b32_e32 v96, v0
	v_mov_b32_e32 v97, v0
	v_mov_b32_e32 v98, v0
	v_mov_b32_e32 v99, v0
	v_mov_b32_e32 v104, v0
	v_mov_b32_e32 v105, v0
	v_mov_b32_e32 v106, v0
	v_mov_b32_e32 v107, v0
	v_mov_b32_e32 v112, v0
	v_mov_b32_e32 v113, v0
	v_mov_b32_e32 v114, v0
	v_mov_b32_e32 v115, v0
	v_mov_b32_e32 v120, v0
	v_mov_b32_e32 v121, v0
	v_mov_b32_e32 v122, v0
	v_mov_b32_e32 v123, v0
	v_mov_b32_e32 v124, v0
	v_mov_b32_e32 v125, v0
	v_mov_b32_e32 v126, v0
	v_mov_b32_e32 v127, v0
	s_cmp_eq_u32 s3, 1
	s_cbranch_scc1 .LBB0_219
	s_add_u32 s16, s6, 0xfffc0080
	s_addc_u32 s17, s7, -1
	s_add_i32 s21, 0, 0x10000
	s_cmp_eq_u32 s20, 12
	s_cselect_b32 s27, s99, s17
	s_cselect_b32 s26, vcc_lo, s16
	s_cselect_b32 s17, s5, s47
	s_cselect_b32 s16, vcc_hi, s46
	s_add_i32 s52, 0, 0x14000
	v_add_u32_e32 v140, s21, v218
	v_add_u32_e32 v156, s52, v218
	ds_read_b128 v[128:131], v140
	ds_read_b128 v[132:135], v140 offset:1024
	ds_read_b128 v[136:139], v140 offset:2048
	ds_read_b128 v[140:143], v140 offset:3072
	ds_read_b128 v[144:147], v156
	ds_read_b128 v[148:151], v156 offset:1024
	ds_read_b128 v[152:155], v156 offset:2048
	ds_read_b128 v[156:159], v156 offset:3072
	v_lshl_add_u64 v[244:245], s[6:7], 0, v[180:181]
	s_add_i32 m0, s57, 0xc000
	ds_read_b128 v[184:187], v226
	ds_read_b128 v[188:191], v226 offset:1024
	ds_read_b128 v[192:195], v226 offset:2048
	ds_read_b128 v[196:199], v226 offset:3072
	ds_read_b128 v[228:231], v226 offset:4096
	ds_read_b128 v[232:235], v226 offset:5120
	ds_read_b128 v[236:239], v226 offset:6144
	ds_read_b128 v[240:243], v226 offset:7168
	global_load_lds_dwordx4 v[244:245], off
	v_lshl_add_u64 v[244:245], s[6:7], 0, v[182:183]
	s_add_i32 m0, s57, 0xe000
	s_nop 0
	global_load_lds_dwordx4 v[244:245], off
	s_waitcnt vmcnt(24)
	s_waitcnt lgkmcnt(0)
	s_barrier
; #define PG8_STAGE(bufoff, gbase, voff) do { _Pragma("unroll") for (int _i = 0; _i < 2; ++_i) \
;         __builtin_amdgcn_global_load_lds((const unsigned*)((const char*)(gbase) + (voff)[_i]), (PG8_LAS unsigned*)(lds + (bufoff) + ldsw + _i * 8192), 16, 0, 0); } while (0)
; #define PG8_LDA(dst, b, h) do { _Pragma("unroll") for (int m = 0; m < 4; ++m) _Pragma("unroll") for (int k = 0; k < 2; ++k) dst[m][k] = *(const PG8_LAS bf16x8*)(lds + PG8_SA(b, h) + aoff + m * 2048 + k * 1024); } while (0)
; #define PG8_LDB(dst, b, h) do { _Pragma("unroll") for (int n = 0; n < 2; ++n) _Pragma("unroll") for (int k = 0; k < 2; ++k) dst[n][k] = *(const PG8_LAS bf16x8*)(lds + PG8_SB(b, h) + boff + n * 2048 + k * 1024); } while (0)
; #define PG8_MMA(ai, bj, At, Bt) do { __builtin_amdgcn_s_setprio(1); _Pragma("unroll") for (int m = 0; m < 4; ++m) _Pragma("unroll") for (int n = 0; n < 2; ++n) _Pragma("unroll") for (int k = 0; k < 2; ++k) \
;         acc[ai][bj][m][n] = __builtin_amdgcn_mfma_f32_16x16x32_bf16(Bt[n][k], At[m][k], acc[ai][bj][m][n], 0, 0, 0); __builtin_amdgcn_s_setprio(0); } while (0)
; #define PG8_WAIT_V(n) asm volatile("s_waitcnt vmcnt(" #n ")" ::: "memory")
; #define PG8_WAIT_L(n) asm volatile("s_waitcnt lgkmcnt(" #n ")" ::: "memory")
; #define PG8_BAR __builtin_amdgcn_s_barrier()
; #define PG8_SCHED __builtin_amdgcn_sched_barrier(0)
; template <class Epi, class Sched, bool ALIGN_EPI = false, bool SP2 = false>
; __device__ __forceinline__ void gemm_phase(PG8_LAS unsigned char* lds, const Gemm g, const Sched& S, const Epi& E) {
;     ...
;             PG8_LDB(B0, 0, 0); PG8_LDB(B1, 0, 1); PG8_SCHED; PG8_LDA(At, 0, 0); PG8_STAGE(PG8_SA(1, 1), a1 + hstep, voffA);
;             PG8_WAIT_V(8); PG8_WAIT_L(0); PG8_BAR; PG8_MMA(0, 0, At, B0); PG8_MMA(0, 1, At, B1); PG8_BAR; PG8_SCHED;
;             PG8_LDA(At, 0, 1); PG8_STAGE(PG8_SB(0, 0), b2, voffB); PG8_STAGE(PG8_SB(0, 1), b2 + hstep, voffB); PG8_STAGE(PG8_SA(0, 0), a2, voffA);
;             PG8_WAIT_V(8); PG8_WAIT_L(0); PG8_BAR; PG8_MMA(1, 0, At, B0); PG8_MMA(1, 1, At, B1); PG8_BAR; PG8_SCHED;
	s_setprio 1
	s_waitcnt lgkmcnt(0)
	v_mfma_f32_16x16x32_bf16 v[124:127], v[128:131], v[184:187], v[124:127]
	v_mfma_f32_16x16x32_bf16 v[120:123], v[136:139], v[184:187], v[120:123]
	v_mfma_f32_16x16x32_bf16 v[112:115], v[128:131], v[192:195], v[112:115]
	v_mfma_f32_16x16x32_bf16 v[104:107], v[136:139], v[192:195], v[104:107]
	v_mfma_f32_16x16x32_bf16 v[96:99], v[128:131], v[228:231], v[96:99]
	v_mfma_f32_16x16x32_bf16 v[88:91], v[136:139], v[228:231], v[88:91]
	v_mfma_f32_16x16x32_bf16 v[80:83], v[128:131], v[236:239], v[80:83]
	v_mfma_f32_16x16x32_bf16 v[72:75], v[136:139], v[236:239], v[72:75]
	v_mfma_f32_16x16x32_bf16 v[124:127], v[132:135], v[188:191], v[124:127]
	v_mfma_f32_16x16x32_bf16 v[120:123], v[140:143], v[188:191], v[120:123]
	v_mfma_f32_16x16x32_bf16 v[112:115], v[132:135], v[196:199], v[112:115]
	v_mfma_f32_16x16x32_bf16 v[104:107], v[140:143], v[196:199], v[104:107]
	v_mfma_f32_16x16x32_bf16 v[96:99], v[132:135], v[232:235], v[96:99]
	v_mfma_f32_16x16x32_bf16 v[88:91], v[140:143], v[232:235], v[88:91]
	v_mfma_f32_16x16x32_bf16 v[80:83], v[132:135], v[240:243], v[80:83]
	v_mfma_f32_16x16x32_bf16 v[72:75], v[140:143], v[240:243], v[72:75]
	s_setprio 0
	s_setprio 1
	v_mfma_f32_16x16x32_bf16 v[116:119], v[144:147], v[184:187], v[116:119]
	v_mfma_f32_16x16x32_bf16 v[108:111], v[152:155], v[184:187], v[108:111]
	v_mfma_f32_16x16x32_bf16 v[100:103], v[144:147], v[192:195], v[100:103]
	v_mfma_f32_16x16x32_bf16 v[92:95], v[152:155], v[192:195], v[92:95]
	v_mfma_f32_16x16x32_bf16 v[84:87], v[144:147], v[228:231], v[84:87]
	v_mfma_f32_16x16x32_bf16 v[76:79], v[152:155], v[228:231], v[76:79]
	v_mfma_f32_16x16x32_bf16 v[68:71], v[144:147], v[236:239], v[68:71]
	v_mfma_f32_16x16x32_bf16 v[64:67], v[152:155], v[236:239], v[64:67]
	v_mfma_f32_16x16x32_bf16 v[116:119], v[148:151], v[188:191], v[116:119]
	v_mfma_f32_16x16x32_bf16 v[108:111], v[156:159], v[188:191], v[108:111]
	v_mfma_f32_16x16x32_bf16 v[100:103], v[148:151], v[196:199], v[100:103]
	v_mfma_f32_16x16x32_bf16 v[92:95], v[156:159], v[196:199], v[92:95]
	v_mfma_f32_16x16x32_bf16 v[84:87], v[148:151], v[232:235], v[84:87]
	v_mfma_f32_16x16x32_bf16 v[76:79], v[156:159], v[232:235], v[76:79]
	v_mfma_f32_16x16x32_bf16 v[68:71], v[148:151], v[240:243], v[68:71]
	v_mfma_f32_16x16x32_bf16 v[64:67], v[156:159], v[240:243], v[64:67]
	s_setprio 0
	s_barrier
	s_add_i32 s21, s21, s51
	v_lshl_add_u64 v[244:245], s[16:17], 0, v[166:167]
	s_mov_b32 m0, s21
	ds_read_b128 v[184:187], v226 offset:16384
	ds_read_b128 v[188:191], v226 offset:17408
	ds_read_b128 v[192:195], v226 offset:18432
	ds_read_b128 v[196:199], v226 offset:19456
	ds_read_b128 v[228:231], v226 offset:20480
	ds_read_b128 v[232:235], v226 offset:21504
	ds_read_b128 v[236:239], v226 offset:22528
	ds_read_b128 v[240:243], v226 offset:23552
	global_load_lds_dwordx4 v[244:245], off
	s_add_i32 m0, s21, 0x2000
	s_add_u32 s22, s16, 0x40000
	v_lshl_add_u64 v[246:247], s[16:17], 0, v[162:163]
	s_addc_u32 s23, s17, 0
	s_add_i32 s21, s52, s51
	global_load_lds_dwordx4 v[246:247], off
	v_lshl_add_u64 v[248:249], s[22:23], 0, v[166:167]
	s_mov_b32 m0, s21
	v_lshl_add_u64 v[250:251], s[26:27], 0, v[164:165]
	global_load_lds_dwordx4 v[248:249], off
	v_lshl_add_u64 v[248:249], s[22:23], 0, v[162:163]
	s_add_i32 m0, s21, 0x2000
	s_nop 0
	global_load_lds_dwordx4 v[248:249], off
	v_lshl_add_u64 v[248:249], s[26:27], 0, v[168:169]
	s_mov_b32 m0, s57
	s_nop 0
	global_load_lds_dwordx4 v[248:249], off
	s_mov_b32 m0, s84
	s_nop 0
	global_load_lds_dwordx4 v[250:251], off
	s_waitcnt vmcnt(24)
	s_waitcnt lgkmcnt(0)
	s_barrier
	s_setprio 1
	s_waitcnt lgkmcnt(0)
	v_mfma_f32_16x16x32_bf16 v[60:63], v[128:131], v[184:187], v[60:63]
	v_mfma_f32_16x16x32_bf16 v[56:59], v[136:139], v[184:187], v[56:59]
	v_mfma_f32_16x16x32_bf16 v[48:51], v[128:131], v[192:195], v[48:51]
	v_mfma_f32_16x16x32_bf16 v[40:43], v[136:139], v[192:195], v[40:43]
	v_mfma_f32_16x16x32_bf16 v[32:35], v[128:131], v[228:231], v[32:35]
	v_mfma_f32_16x16x32_bf16 v[24:27], v[136:139], v[228:231], v[24:27]
	v_mfma_f32_16x16x32_bf16 v[16:19], v[128:131], v[236:239], v[16:19]
	v_mfma_f32_16x16x32_bf16 v[8:11], v[136:139], v[236:239], v[8:11]
	v_mfma_f32_16x16x32_bf16 v[60:63], v[132:135], v[188:191], v[60:63]
	v_mfma_f32_16x16x32_bf16 v[56:59], v[140:143], v[188:191], v[56:59]
	v_mfma_f32_16x16x32_bf16 v[48:51], v[132:135], v[196:199], v[48:51]
	v_mfma_f32_16x16x32_bf16 v[40:43], v[140:143], v[196:199], v[40:43]
	v_mfma_f32_16x16x32_bf16 v[32:35], v[132:135], v[232:235], v[32:35]
	v_mfma_f32_16x16x32_bf16 v[24:27], v[140:143], v[232:235], v[24:27]
	v_mfma_f32_16x16x32_bf16 v[16:19], v[132:135], v[240:243], v[16:19]
	v_mfma_f32_16x16x32_bf16 v[8:11], v[140:143], v[240:243], v[8:11]
	s_setprio 0
	s_setprio 1
	v_mfma_f32_16x16x32_bf16 v[52:55], v[144:147], v[184:187], v[52:55]
	v_mfma_f32_16x16x32_bf16 v[44:47], v[152:155], v[184:187], v[44:47]
	v_mfma_f32_16x16x32_bf16 v[36:39], v[144:147], v[192:195], v[36:39]
	v_mfma_f32_16x16x32_bf16 v[28:31], v[152:155], v[192:195], v[28:31]
	v_mfma_f32_16x16x32_bf16 v[20:23], v[144:147], v[228:231], v[20:23]
	v_mfma_f32_16x16x32_bf16 v[12:15], v[152:155], v[228:231], v[12:15]
	v_mfma_f32_16x16x32_bf16 v[4:7], v[144:147], v[236:239], v[4:7]
	v_mfma_f32_16x16x32_bf16 v[0:3], v[152:155], v[236:239], v[0:3]
	v_mfma_f32_16x16x32_bf16 v[52:55], v[148:151], v[188:191], v[52:55]
	v_mfma_f32_16x16x32_bf16 v[44:47], v[156:159], v[188:191], v[44:47]
	v_mfma_f32_16x16x32_bf16 v[36:39], v[148:151], v[196:199], v[36:39]
	v_mfma_f32_16x16x32_bf16 v[28:31], v[156:159], v[196:199], v[28:31]
	v_mfma_f32_16x16x32_bf16 v[20:23], v[148:151], v[232:235], v[20:23]
	v_mfma_f32_16x16x32_bf16 v[12:15], v[156:159], v[232:235], v[12:15]
	v_mfma_f32_16x16x32_bf16 v[4:7], v[148:151], v[240:243], v[4:7]
	v_mfma_f32_16x16x32_bf16 v[0:3], v[156:159], v[240:243], v[0:3]
	s_setprio 0
	s_barrier
; #define PG8_STAGE(bufoff, gbase, voff) do { _Pragma("unroll") for (int _i = 0; _i < 2; ++_i) \
;         __builtin_amdgcn_global_load_lds((const unsigned*)((const char*)(gbase) + (voff)[_i]), (PG8_LAS unsigned*)(lds + (bufoff) + ldsw + _i * 8192), 16, 0, 0); } while (0)
; #define PG8_LDA(dst, b, h) do { _Pragma("unroll") for (int m = 0; m < 4; ++m) _Pragma("unroll") for (int k = 0; k < 2; ++k) dst[m][k] = *(const PG8_LAS bf16x8*)(lds + PG8_SA(b, h) + aoff + m * 2048 + k * 1024); } while (0)
; #define PG8_LDB(dst, b, h) do { _Pragma("unroll") for (int n = 0; n < 2; ++n) _Pragma("unroll") for (int k = 0; k < 2; ++k) dst[n][k] = *(const PG8_LAS bf16x8*)(lds + PG8_SB(b, h) + boff + n * 2048 + k * 1024); } while (0)
; #define PG8_MMA(ai, bj, At, Bt) do { __builtin_amdgcn_s_setprio(1); _Pragma("unroll") for (int m = 0; m < 4; ++m) _Pragma("unroll") for (int n = 0; n < 2; ++n) _Pragma("unroll") for (int k = 0; k < 2; ++k) \
;         acc[ai][bj][m][n] = __builtin_amdgcn_mfma_f32_16x16x32_bf16(Bt[n][k], At[m][k], acc[ai][bj][m][n], 0, 0, 0); __builtin_amdgcn_s_setprio(0); } while (0)
; #define PG8_WAIT_V(n) asm volatile("s_waitcnt vmcnt(" #n ")" ::: "memory")
; #define PG8_WAIT_L(n) asm volatile("s_waitcnt lgkmcnt(" #n ")" ::: "memory")
; #define PG8_BAR __builtin_amdgcn_s_barrier()
; #define PG8_SCHED __builtin_amdgcn_sched_barrier(0)
; template <class Epi, class Sched, bool ALIGN_EPI = false, bool SP2 = false>
; __device__ __forceinline__ void gemm_phase(PG8_LAS unsigned char* lds, const Gemm g, const Sched& S, const Epi& E) {
;     ...
;             PG8_LDB(B0, 1, 0); PG8_LDB(B1, 1, 1); PG8_SCHED; PG8_LDA(At, 1, 0); PG8_STAGE(PG8_SA(0, 1), a2 + hstep, voffA);
;             PG8_WAIT_V(8); PG8_WAIT_L(0); PG8_BAR; PG8_MMA(0, 0, At, B0); PG8_MMA(0, 1, At, B1); PG8_BAR; PG8_SCHED;
	s_add_i32 s21, 0, 0x18000
	s_add_i32 s52, 0, 0x1c000
	v_add_u32_e32 v140, s21, v218
	v_add_u32_e32 v156, s52, v218
	ds_read_b128 v[128:131], v140
	ds_read_b128 v[132:135], v140 offset:1024
	ds_read_b128 v[136:139], v140 offset:2048
	ds_read_b128 v[140:143], v140 offset:3072
	ds_read_b128 v[144:147], v156
	ds_read_b128 v[148:151], v156 offset:1024
	ds_read_b128 v[152:155], v156 offset:2048
	ds_read_b128 v[156:159], v156 offset:3072
	s_add_u32 s22, s26, 0x40000
	s_addc_u32 s23, s27, 0
	s_mov_b32 m0, s85
	v_lshl_add_u64 v[252:253], s[22:23], 0, v[168:169]
	ds_read_b128 v[184:187], v226 offset:32768
	ds_read_b128 v[188:191], v226 offset:33792
	ds_read_b128 v[192:195], v226 offset:34816
	ds_read_b128 v[196:199], v226 offset:35840
	ds_read_b128 v[228:231], v226 offset:36864
	ds_read_b128 v[232:235], v226 offset:37888
	ds_read_b128 v[236:239], v226 offset:38912
	ds_read_b128 v[240:243], v226 offset:39936
	global_load_lds_dwordx4 v[252:253], off
	v_lshl_add_u64 v[252:253], s[22:23], 0, v[164:165]
	s_mov_b32 m0, s93
	s_nop 0
	global_load_lds_dwordx4 v[252:253], off
	s_waitcnt vmcnt(8)
	s_waitcnt lgkmcnt(0)
	s_barrier
	s_setprio 1
	s_waitcnt lgkmcnt(0)
	v_mfma_f32_16x16x32_bf16 v[124:127], v[128:131], v[184:187], v[124:127]
	v_mfma_f32_16x16x32_bf16 v[120:123], v[136:139], v[184:187], v[120:123]
	v_mfma_f32_16x16x32_bf16 v[112:115], v[128:131], v[192:195], v[112:115]
	v_mfma_f32_16x16x32_bf16 v[104:107], v[136:139], v[192:195], v[104:107]
	v_mfma_f32_16x16x32_bf16 v[96:99], v[128:131], v[228:231], v[96:99]
	v_mfma_f32_16x16x32_bf16 v[88:91], v[136:139], v[228:231], v[88:91]
	v_mfma_f32_16x16x32_bf16 v[80:83], v[128:131], v[236:239], v[80:83]
	v_mfma_f32_16x16x32_bf16 v[72:75], v[136:139], v[236:239], v[72:75]
	v_mfma_f32_16x16x32_bf16 v[124:127], v[132:135], v[188:191], v[124:127]
	v_mfma_f32_16x16x32_bf16 v[120:123], v[140:143], v[188:191], v[120:123]
	v_mfma_f32_16x16x32_bf16 v[112:115], v[132:135], v[196:199], v[112:115]
	v_mfma_f32_16x16x32_bf16 v[104:107], v[140:143], v[196:199], v[104:107]
	v_mfma_f32_16x16x32_bf16 v[96:99], v[132:135], v[232:235], v[96:99]
	v_mfma_f32_16x16x32_bf16 v[88:91], v[140:143], v[232:235], v[88:91]
	v_mfma_f32_16x16x32_bf16 v[80:83], v[132:135], v[240:243], v[80:83]
	v_mfma_f32_16x16x32_bf16 v[72:75], v[140:143], v[240:243], v[72:75]
	s_setprio 0
	s_setprio 1
	v_mfma_f32_16x16x32_bf16 v[116:119], v[144:147], v[184:187], v[116:119]
	v_mfma_f32_16x16x32_bf16 v[108:111], v[152:155], v[184:187], v[108:111]
	v_mfma_f32_16x16x32_bf16 v[100:103], v[144:147], v[192:195], v[100:103]
	v_mfma_f32_16x16x32_bf16 v[92:95], v[152:155], v[192:195], v[92:95]
	v_mfma_f32_16x16x32_bf16 v[84:87], v[144:147], v[228:231], v[84:87]
	v_mfma_f32_16x16x32_bf16 v[76:79], v[152:155], v[228:231], v[76:79]
	v_mfma_f32_16x16x32_bf16 v[68:71], v[144:147], v[236:239], v[68:71]
	v_mfma_f32_16x16x32_bf16 v[64:67], v[152:155], v[236:239], v[64:67]
	v_mfma_f32_16x16x32_bf16 v[116:119], v[148:151], v[188:191], v[116:119]
	v_mfma_f32_16x16x32_bf16 v[108:111], v[156:159], v[188:191], v[108:111]
	v_mfma_f32_16x16x32_bf16 v[100:103], v[148:151], v[196:199], v[100:103]
	v_mfma_f32_16x16x32_bf16 v[92:95], v[156:159], v[196:199], v[92:95]
	v_mfma_f32_16x16x32_bf16 v[84:87], v[148:151], v[232:235], v[84:87]
	v_mfma_f32_16x16x32_bf16 v[76:79], v[156:159], v[232:235], v[76:79]
	v_mfma_f32_16x16x32_bf16 v[68:71], v[148:151], v[240:243], v[68:71]
	v_mfma_f32_16x16x32_bf16 v[64:67], v[156:159], v[240:243], v[64:67]
	s_setprio 0
	s_barrier
; #define PG8_STAGE(bufoff, gbase, voff) do { _Pragma("unroll") for (int _i = 0; _i < 2; ++_i) \
;         __builtin_amdgcn_global_load_lds((const unsigned*)((const char*)(gbase) + (voff)[_i]), (PG8_LAS unsigned*)(lds + (bufoff) + ldsw + _i * 8192), 16, 0, 0); } while (0)
; #define PG8_LDA(dst, b, h) do { _Pragma("unroll") for (int m = 0; m < 4; ++m) _Pragma("unroll") for (int k = 0; k < 2; ++k) dst[m][k] = *(const PG8_LAS bf16x8*)(lds + PG8_SA(b, h) + aoff + m * 2048 + k * 1024); } while (0)
; #define PG8_MMA(ai, bj, At, Bt) do { __builtin_amdgcn_s_setprio(1); _Pragma("unroll") for (int m = 0; m < 4; ++m) _Pragma("unroll") for (int n = 0; n < 2; ++n) _Pragma("unroll") for (int k = 0; k < 2; ++k) \
;         acc[ai][bj][m][n] = __builtin_amdgcn_mfma_f32_16x16x32_bf16(Bt[n][k], At[m][k], acc[ai][bj][m][n], 0, 0, 0); __builtin_amdgcn_s_setprio(0); } while (0)
; #define PG8_WAIT_V(n) asm volatile("s_waitcnt vmcnt(" #n ")" ::: "memory")
; #define PG8_WAIT_L(n) asm volatile("s_waitcnt lgkmcnt(" #n ")" ::: "memory")
; #define PG8_BAR __builtin_amdgcn_s_barrier()
; #define PG8_SCHED __builtin_amdgcn_sched_barrier(0)
; template <class Epi, class Sched, bool ALIGN_EPI = false, bool SP2 = false>
; __device__ __forceinline__ void gemm_phase(PG8_LAS unsigned char* lds, const Gemm g, const Sched& S, const Epi& E) {
;     ...
;         for (int t = 0; t < nt; t += 2) {
;             const bool last = (t == nt - 2);
;             const char* a1 = cA + (size_t)(t + 1) * kstep;
;             const char* a2 = last ? nA : cA + (size_t)(t + 2) * kstep; const char* b2 = last ? nB : cB + (size_t)(t + 2) * kstep;
;     ...
;             PG8_LDA(At, 1, 1); PG8_STAGE(PG8_SB(1, 0), b3, voffB); PG8_STAGE(PG8_SB(1, 1), b3 + hstep, voffB); PG8_STAGE(PG8_SA(1, 0), a3, voffA);
;             PG8_WAIT_V(8); PG8_WAIT_L(0); PG8_BAR; PG8_MMA(1, 0, At, B0); PG8_MMA(1, 1, At, B1); PG8_BAR; PG8_SCHED;
	s_add_i32 s21, s21, s51
	v_lshl_add_u64 v[244:245], v[244:245], 0, s[90:91]
	s_mov_b32 m0, s21
	ds_read_b128 v[184:187], v226 offset:49152
	ds_read_b128 v[188:191], v226 offset:50176
	ds_read_b128 v[192:195], v226 offset:51200
	ds_read_b128 v[196:199], v226 offset:52224
	ds_read_b128 v[228:231], v226 offset:53248
	ds_read_b128 v[232:235], v226 offset:54272
	ds_read_b128 v[236:239], v226 offset:55296
	ds_read_b128 v[240:243], v226 offset:56320
	global_load_lds_dwordx4 v[244:245], off
	s_add_i32 m0, s21, 0x2000
	s_add_u32 s16, s16, 0x40080
	v_lshl_add_u64 v[244:245], v[246:247], 0, s[90:91]
	s_addc_u32 s17, s17, 0
	s_add_i32 s21, s52, s51
	global_load_lds_dwordx4 v[244:245], off
	v_lshl_add_u64 v[244:245], s[16:17], 0, v[166:167]
	s_mov_b32 m0, s21
	s_nop 0
	global_load_lds_dwordx4 v[244:245], off
	v_lshl_add_u64 v[244:245], s[16:17], 0, v[162:163]
	s_add_i32 m0, s21, 0x2000
	s_nop 0
	global_load_lds_dwordx4 v[244:245], off
	v_lshl_add_u64 v[244:245], v[248:249], 0, s[90:91]
	s_mov_b32 m0, s19
	s_nop 0
	global_load_lds_dwordx4 v[244:245], off
	v_lshl_add_u64 v[244:245], v[250:251], 0, s[90:91]
	s_mov_b32 m0, s80
	s_nop 0
	global_load_lds_dwordx4 v[244:245], off
	s_waitcnt vmcnt(8)
	s_waitcnt lgkmcnt(0)
	s_barrier
	s_setprio 1
	s_waitcnt lgkmcnt(0)
	v_mfma_f32_16x16x32_bf16 v[60:63], v[128:131], v[184:187], v[60:63]
	v_mfma_f32_16x16x32_bf16 v[56:59], v[136:139], v[184:187], v[56:59]
	v_mfma_f32_16x16x32_bf16 v[48:51], v[128:131], v[192:195], v[48:51]
	v_mfma_f32_16x16x32_bf16 v[40:43], v[136:139], v[192:195], v[40:43]
	v_mfma_f32_16x16x32_bf16 v[32:35], v[128:131], v[228:231], v[32:35]
	v_mfma_f32_16x16x32_bf16 v[24:27], v[136:139], v[228:231], v[24:27]
	v_mfma_f32_16x16x32_bf16 v[16:19], v[128:131], v[236:239], v[16:19]
	v_mfma_f32_16x16x32_bf16 v[8:11], v[136:139], v[236:239], v[8:11]
	v_mfma_f32_16x16x32_bf16 v[60:63], v[132:135], v[188:191], v[60:63]
	v_mfma_f32_16x16x32_bf16 v[56:59], v[140:143], v[188:191], v[56:59]
	v_mfma_f32_16x16x32_bf16 v[48:51], v[132:135], v[196:199], v[48:51]
	v_mfma_f32_16x16x32_bf16 v[40:43], v[140:143], v[196:199], v[40:43]
	v_mfma_f32_16x16x32_bf16 v[32:35], v[132:135], v[232:235], v[32:35]
	v_mfma_f32_16x16x32_bf16 v[24:27], v[140:143], v[232:235], v[24:27]
	v_mfma_f32_16x16x32_bf16 v[16:19], v[132:135], v[240:243], v[16:19]
	v_mfma_f32_16x16x32_bf16 v[8:11], v[140:143], v[240:243], v[8:11]
	s_setprio 0
	s_setprio 1
	v_mfma_f32_16x16x32_bf16 v[52:55], v[144:147], v[184:187], v[52:55]
	v_mfma_f32_16x16x32_bf16 v[44:47], v[152:155], v[184:187], v[44:47]
	v_mfma_f32_16x16x32_bf16 v[36:39], v[144:147], v[192:195], v[36:39]
	v_mfma_f32_16x16x32_bf16 v[28:31], v[152:155], v[192:195], v[28:31]
	v_mfma_f32_16x16x32_bf16 v[20:23], v[144:147], v[228:231], v[20:23]
	v_mfma_f32_16x16x32_bf16 v[12:15], v[152:155], v[228:231], v[12:15]
	v_mfma_f32_16x16x32_bf16 v[4:7], v[144:147], v[236:239], v[4:7]
	v_mfma_f32_16x16x32_bf16 v[0:3], v[152:155], v[236:239], v[0:3]
	v_mfma_f32_16x16x32_bf16 v[52:55], v[148:151], v[188:191], v[52:55]
	v_mfma_f32_16x16x32_bf16 v[44:47], v[156:159], v[188:191], v[44:47]
	v_mfma_f32_16x16x32_bf16 v[36:39], v[148:151], v[196:199], v[36:39]
	v_mfma_f32_16x16x32_bf16 v[28:31], v[156:159], v[196:199], v[28:31]
	v_mfma_f32_16x16x32_bf16 v[20:23], v[148:151], v[232:235], v[20:23]
	v_mfma_f32_16x16x32_bf16 v[12:15], v[156:159], v[232:235], v[12:15]
	v_mfma_f32_16x16x32_bf16 v[4:7], v[148:151], v[240:243], v[4:7]
	v_mfma_f32_16x16x32_bf16 v[0:3], v[156:159], v[240:243], v[0:3]
	s_setprio 0
	s_barrier
	s_add_i32 s20, s20, 2
	s_add_u32 s6, s6, 0x100
	s_addc_u32 s7, s7, 0
	s_add_u32 s46, s46, 0x100
	s_addc_u32 s47, s47, 0
	s_cmp_gt_u32 s20, 13
	s_cbranch_scc0 .LBB0_219
	s_branch .Lpeel_after_LBB0219
